# latent attention: static s_setprio 1 for the lagging wave half (waves 4-7)
# speedup vs baseline: 1.0000x; 1.0000x over previous
; DEV void attn_item(const Params& p, int bl, int head, int q0, int nkeys, char* smem, int tid) {
;     ...
;   for (int t = 0; t < nt; ++t) {
;     if (t + 1 < nt) {
; #pragma unroll
;       for (int i = 0; i < 3; ++i) kr[i] = *(const u32x4*)(Kg + (long)(t + 1) * 128 * 96 + (long)(i * 512 + tid) * 8);
; #pragma unroll
;       for (int i = 0; i < 2; ++i) vr[i] = *(const u32x4*)(Vg + (t + 1) * 128 + voffg[i]);
;     }
;     const char* kb = smem + (t & 1) * ASTG;
;     const char* vb = kb + KBYTES;
; #pragma unroll
;     for (int hh = 0; hh < 2; ++hh) {
;       f32x4 s[4][2];
; #pragma unroll
;       for (int kf = 0; kf < 4; ++kf) {
; #pragma unroll
;         for (int ks = 0; ks < 3; ++ks) {
;           bf16x8 a = *(const bf16x8*)(kb + (hh * 64 + kf * 16 + fr) * KROW + ks * 64 + fq * 16);
;           s[kf][0] = __builtin_amdgcn_mfma_f32_16x16x32_bf16(a, qf[0][ks], ks == 0 ? negm[0] : s[kf][0], 0, 0, 0);
;           s[kf][1] = __builtin_amdgcn_mfma_f32_16x16x32_bf16(a, qf[1][ks], ks == 0 ? negm[1] : s[kf][1], 0, 0, 0);
;         }
;       }
; #pragma unroll
;       for (int kk = 0; kk < 2; ++kk) {
;         bf16x8 pb[2];
; #pragma unroll
;         for (int qt = 0; qt < 2; ++qt) {
;           const float e0 = ex2(s[2 * kk][qt][0]), e1 = ex2(s[2 * kk][qt][1]), e2 = ex2(s[2 * kk][qt][2]), e3 = ex2(s[2 * kk][qt][3]);
;           const float e4 = ex2(s[2 * kk + 1][qt][0]), e5 = ex2(s[2 * kk + 1][qt][1]), e6 = ex2(s[2 * kk + 1][qt][2]), e7 = ex2(s[2 * kk + 1][qt][3]);
;           u32x4 cw = {pack2(e0, e1), pack2(e2, e3), pack2(e4, e5), pack2(e6, e7)};
;           pb[qt] = __builtin_bit_cast(bf16x8, cw);
;         }
;         lacc[0] = __builtin_amdgcn_mfma_f32_16x16x32_bf16(ones, pb[0], lacc[0], 0, 0, 0);
;         lacc[1] = __builtin_amdgcn_mfma_f32_16x16x32_bf16(ones, pb[1], lacc[1], 0, 0, 0);
; #pragma unroll
;         for (int dvf = 0; dvf < 4; ++dvf) {
;           const char* vp = vb + (dvf * 16 + fr) * VROW + (hh * 64 + kk * 32 + fq * 4) * 2;
;           const uint2 h0 = *(const uint2*)vp, h1 = *(const uint2*)(vp + 32);
;           u32x4 vw = {h0.x, h0.y, h1.x, h1.y};
;           const bf16x8 va = __builtin_bit_cast(bf16x8, vw);
;           o[dvf][0] = __builtin_amdgcn_mfma_f32_16x16x32_bf16(va, pb[0], o[dvf][0], 0, 0, 0);
;           o[dvf][1] = __builtin_amdgcn_mfma_f32_16x16x32_bf16(va, pb[1], o[dvf][1], 0, 0, 0);
;         }
.Lattn_b_pre:
	s_setprio 1
	global_load_dwordx4 v[230:233], v[164:165], off
	global_load_dwordx4 v[234:237], v[166:167], off
	global_load_dwordx4 v[238:241], v[168:169], off
	global_load_dwordx4 v[242:245], v[170:171], off
	global_load_dwordx4 v[246:249], v[172:173], off
	v_lshl_add_u64 v[164:165], v[164:165], 0, s[26:27]
	v_lshl_add_u64 v[166:167], v[166:167], 0, s[26:27]
	v_lshl_add_u64 v[168:169], v[168:169], 0, s[16:17]
	v_lshl_add_u64 v[170:171], v[170:171], 0, s[16:17]
	v_lshl_add_u64 v[172:173], v[172:173], 0, s[16:17]
	v_add_u32_e32 v184, s9, v190
	v_add_u32_e32 v185, s9, v191
	v_add_u32_e32 v186, s9, v192
	v_add_u32_e32 v187, s9, v160
	v_add_u32_e32 v188, s9, v162
	s_waitcnt vmcnt(0)
	ds_write_b128 v184, v[238:241]
	ds_write_b128 v185, v[242:245]
	ds_write_b128 v186, v[246:249]
	ds_write_b128 v187, v[230:233] offset:28672
	ds_write_b128 v188, v[234:237] offset:28672
	v_add3_u32 v179, s12, v156, v178
	ds_read_b128 v[198:201], v179
	ds_read_b128 v[202:205], v179 offset:3328
	ds_read_b128 v[206:209], v179 offset:6656
	ds_read_b128 v[210:213], v179 offset:9984
	ds_read_b128 v[214:217], v179 offset:64
	ds_read_b128 v[218:221], v179 offset:3392
	ds_read_b128 v[222:225], v179 offset:6720
	ds_read_b128 v[226:229], v179 offset:10048
	s_waitcnt lgkmcnt(7)
	v_mfma_f32_16x16x32_bf16 v[72:75], v[198:201], v[12:15], v[24:27]
	v_mfma_f32_16x16x32_bf16 v[76:79], v[198:201], v[20:23], v[28:31]
	ds_read_b128 v[198:201], v179 offset:128
	s_waitcnt lgkmcnt(7)
	v_mfma_f32_16x16x32_bf16 v[80:83], v[202:205], v[12:15], v[24:27]
	v_mfma_f32_16x16x32_bf16 v[84:87], v[202:205], v[20:23], v[28:31]
	ds_read_b128 v[202:205], v179 offset:3456
	s_waitcnt lgkmcnt(7)
	v_mfma_f32_16x16x32_bf16 v[88:91], v[206:209], v[12:15], v[24:27]
	v_mfma_f32_16x16x32_bf16 v[92:95], v[206:209], v[20:23], v[28:31]
	ds_read_b128 v[206:209], v179 offset:6784
	s_waitcnt lgkmcnt(7)
	v_mfma_f32_16x16x32_bf16 v[96:99], v[210:213], v[12:15], v[24:27]
	v_mfma_f32_16x16x32_bf16 v[100:103], v[210:213], v[20:23], v[28:31]
	ds_read_b128 v[210:213], v179 offset:10112
	s_waitcnt lgkmcnt(7)
	v_mfma_f32_16x16x32_bf16 v[72:75], v[214:217], v[8:11], v[72:75]
	v_mfma_f32_16x16x32_bf16 v[76:79], v[214:217], v[16:19], v[76:79]
	ds_read_b128 v[214:217], v179 offset:13312
	s_waitcnt lgkmcnt(7)
	v_mfma_f32_16x16x32_bf16 v[80:83], v[218:221], v[8:11], v[80:83]
	v_mfma_f32_16x16x32_bf16 v[84:87], v[218:221], v[16:19], v[84:87]
	ds_read_b128 v[218:221], v179 offset:16640
	s_waitcnt lgkmcnt(7)
	v_mfma_f32_16x16x32_bf16 v[88:91], v[222:225], v[8:11], v[88:91]
	v_mfma_f32_16x16x32_bf16 v[92:95], v[222:225], v[16:19], v[92:95]
	ds_read_b128 v[222:225], v179 offset:19968
	s_waitcnt lgkmcnt(7)
	v_mfma_f32_16x16x32_bf16 v[96:99], v[226:229], v[8:11], v[96:99]
	v_mfma_f32_16x16x32_bf16 v[100:103], v[226:229], v[16:19], v[100:103]
	ds_read_b128 v[226:229], v179 offset:23296
	s_waitcnt lgkmcnt(7)
	v_mfma_f32_16x16x32_bf16 v[72:75], v[198:201], v[4:7], v[72:75]
	v_mfma_f32_16x16x32_bf16 v[76:79], v[198:201], v[0:3], v[76:79]
	ds_read_b128 v[198:201], v179 offset:13376
	s_waitcnt lgkmcnt(7)
	v_mfma_f32_16x16x32_bf16 v[80:83], v[202:205], v[4:7], v[80:83]
	v_mfma_f32_16x16x32_bf16 v[84:87], v[202:205], v[0:3], v[84:87]
	ds_read_b128 v[202:205], v179 offset:16704
	s_waitcnt lgkmcnt(7)
	v_mfma_f32_16x16x32_bf16 v[88:91], v[206:209], v[4:7], v[88:91]
	v_mfma_f32_16x16x32_bf16 v[92:95], v[206:209], v[0:3], v[92:95]
	ds_read_b128 v[206:209], v179 offset:20032
	s_waitcnt lgkmcnt(7)
	v_mfma_f32_16x16x32_bf16 v[96:99], v[210:213], v[4:7], v[96:99]
	v_mfma_f32_16x16x32_bf16 v[100:103], v[210:213], v[0:3], v[100:103]
	ds_read_b128 v[210:213], v179 offset:23360
	s_waitcnt lgkmcnt(7)
	v_mfma_f32_16x16x32_bf16 v[104:107], v[214:217], v[12:15], v[24:27]
	v_mfma_f32_16x16x32_bf16 v[108:111], v[214:217], v[20:23], v[28:31]
	ds_read_b128 v[214:217], v179 offset:13440
	s_waitcnt lgkmcnt(7)
	v_mfma_f32_16x16x32_bf16 v[112:115], v[218:221], v[12:15], v[24:27]
	v_mfma_f32_16x16x32_bf16 v[116:119], v[218:221], v[20:23], v[28:31]
	ds_read_b128 v[218:221], v179 offset:16768
	s_waitcnt lgkmcnt(7)
	v_mfma_f32_16x16x32_bf16 v[120:123], v[222:225], v[12:15], v[24:27]
	v_exp_f32_e32 v72, v72
	v_mfma_f32_16x16x32_bf16 v[124:127], v[222:225], v[20:23], v[28:31]
	v_exp_f32_e32 v73, v73
	ds_read_b128 v[222:225], v179 offset:20096
	s_waitcnt lgkmcnt(7)
	v_mfma_f32_16x16x32_bf16 v[128:131], v[226:229], v[12:15], v[24:27]
	v_exp_f32_e32 v74, v74
	v_mfma_f32_16x16x32_bf16 v[132:135], v[226:229], v[20:23], v[28:31]
	v_exp_f32_e32 v75, v75
	ds_read_b128 v[226:229], v179 offset:23424
	s_waitcnt lgkmcnt(7)
	v_mfma_f32_16x16x32_bf16 v[104:107], v[198:201], v[8:11], v[104:107]
	v_exp_f32_e32 v80, v80
	v_exp_f32_e32 v81, v81
	v_mfma_f32_16x16x32_bf16 v[108:111], v[198:201], v[16:19], v[108:111]
	v_exp_f32_e32 v82, v82
	s_waitcnt lgkmcnt(6)
	v_mfma_f32_16x16x32_bf16 v[112:115], v[202:205], v[8:11], v[112:115]
	v_exp_f32_e32 v83, v83
	v_mfma_f32_16x16x32_bf16 v[116:119], v[202:205], v[16:19], v[116:119]
	v_exp_f32_e32 v76, v76
	s_waitcnt lgkmcnt(5)
	v_mfma_f32_16x16x32_bf16 v[120:123], v[206:209], v[8:11], v[120:123]
	v_exp_f32_e32 v77, v77
	v_mfma_f32_16x16x32_bf16 v[124:127], v[206:209], v[16:19], v[124:127]
	v_exp_f32_e32 v78, v78
	v_exp_f32_e32 v79, v79
	s_waitcnt lgkmcnt(4)
	v_mfma_f32_16x16x32_bf16 v[128:131], v[210:213], v[8:11], v[128:131]
	v_exp_f32_e32 v84, v84
	v_mfma_f32_16x16x32_bf16 v[132:135], v[210:213], v[16:19], v[132:135]
	v_exp_f32_e32 v85, v85
	s_waitcnt lgkmcnt(3)
	v_mfma_f32_16x16x32_bf16 v[104:107], v[214:217], v[4:7], v[104:107]
	v_exp_f32_e32 v86, v86
	v_mfma_f32_16x16x32_bf16 v[108:111], v[214:217], v[0:3], v[108:111]
	v_exp_f32_e32 v87, v87
	s_waitcnt lgkmcnt(2)
	v_mfma_f32_16x16x32_bf16 v[112:115], v[218:221], v[4:7], v[112:115]
	v_cvt_pk_bf16_f32 v136, v72, v73
	v_cvt_pk_bf16_f32 v137, v74, v75
	v_mfma_f32_16x16x32_bf16 v[116:119], v[218:221], v[0:3], v[116:119]
	v_cvt_pk_bf16_f32 v138, v80, v81
	s_waitcnt lgkmcnt(1)
	v_mfma_f32_16x16x32_bf16 v[120:123], v[222:225], v[4:7], v[120:123]
	v_cvt_pk_bf16_f32 v139, v82, v83
	v_mfma_f32_16x16x32_bf16 v[124:127], v[222:225], v[0:3], v[124:127]
	v_cvt_pk_bf16_f32 v140, v76, v77
	s_waitcnt lgkmcnt(0)
	v_mfma_f32_16x16x32_bf16 v[128:131], v[226:229], v[4:7], v[128:131]
	v_cvt_pk_bf16_f32 v141, v78, v79
	v_mfma_f32_16x16x32_bf16 v[132:135], v[226:229], v[0:3], v[132:135]
	v_cvt_pk_bf16_f32 v142, v84, v85
	v_cvt_pk_bf16_f32 v143, v86, v87
	s_waitcnt lgkmcnt(0)
	s_barrier
; DEV float ex2(float x) { return __builtin_amdgcn_exp2f(x); }
; DEV void attn_item(const Params& p, int bl, int head, int q0, int nkeys, char* smem, int tid) {
;     ...
;       for (int kk = 0; kk < 2; ++kk) {
;         bf16x8 pb[2];
; #pragma unroll
;         for (int qt = 0; qt < 2; ++qt) {
;           const float e0 = ex2(s[2 * kk][qt][0]), e1 = ex2(s[2 * kk][qt][1]), e2 = ex2(s[2 * kk][qt][2]), e3 = ex2(s[2 * kk][qt][3]);
;           const float e4 = ex2(s[2 * kk + 1][qt][0]), e5 = ex2(s[2 * kk + 1][qt][1]), e6 = ex2(s[2 * kk + 1][qt][2]), e7 = ex2(s[2 * kk + 1][qt][3]);
;           u32x4 cw = {pack2(e0, e1), pack2(e2, e3), pack2(e4, e5), pack2(e6, e7)};
;           pb[qt] = __builtin_bit_cast(bf16x8, cw);
;         }
;         lacc[0] = __builtin_amdgcn_mfma_f32_16x16x32_bf16(ones, pb[0], lacc[0], 0, 0, 0);
;         lacc[1] = __builtin_amdgcn_mfma_f32_16x16x32_bf16(ones, pb[1], lacc[1], 0, 0, 0);
; #pragma unroll
;         for (int dvf = 0; dvf < 4; ++dvf) {
;           const char* vp = vb + (dvf * 16 + fr) * VROW + (hh * 64 + kk * 32 + fq * 4) * 2;
;           const uint2 h0 = *(const uint2*)vp, h1 = *(const uint2*)(vp + 32);
;           u32x4 vw = {h0.x, h0.y, h1.x, h1.y};
;           const bf16x8 va = __builtin_bit_cast(bf16x8, vw);
;           o[dvf][0] = __builtin_amdgcn_mfma_f32_16x16x32_bf16(va, pb[0], o[dvf][0], 0, 0, 0);
;           o[dvf][1] = __builtin_amdgcn_mfma_f32_16x16x32_bf16(va, pb[1], o[dvf][1], 0, 0, 0);
;         }
	s_mov_b32 s18, s15
	s_mov_b32 s15, s12
	s_mov_b32 s12, s9
	s_mov_b32 s9, s18
	s_add_i32 s13, s13, 1
	global_load_dwordx4 v[230:233], v[164:165], off
	global_load_dwordx4 v[234:237], v[166:167], off
	global_load_dwordx4 v[238:241], v[168:169], off
	global_load_dwordx4 v[242:245], v[170:171], off
	global_load_dwordx4 v[246:249], v[172:173], off
	v_lshl_add_u64 v[164:165], v[164:165], 0, s[26:27]
	v_lshl_add_u64 v[166:167], v[166:167], 0, s[26:27]
	v_lshl_add_u64 v[168:169], v[168:169], 0, s[16:17]
	v_lshl_add_u64 v[170:171], v[170:171], 0, s[16:17]
	v_lshl_add_u64 v[172:173], v[172:173], 0, s[16:17]
	v_add_u32_e32 v184, s9, v190
	v_add_u32_e32 v185, s9, v191
	v_add_u32_e32 v186, s9, v192
	v_add_u32_e32 v187, s9, v160
	v_add_u32_e32 v188, s9, v162
	v_add3_u32 v180, s15, v176, v177
	ds_read_b64 v[198:199], v180 offset:26624
	ds_read_b64 v[200:201], v180 offset:26656
	ds_read_b64 v[202:203], v180 offset:30976
	ds_read_b64 v[204:205], v180 offset:31008
	ds_read_b64 v[206:207], v180 offset:35328
	ds_read_b64 v[208:209], v180 offset:35360
	ds_read_b64 v[210:211], v180 offset:39680
	ds_read_b64 v[212:213], v180 offset:39712
	ds_read_b64 v[214:215], v180 offset:26688
	ds_read_b64 v[216:217], v180 offset:26720
	ds_read_b64 v[218:219], v180 offset:31040
	ds_read_b64 v[220:221], v180 offset:31072
	ds_read_b64 v[222:223], v180 offset:35392
	ds_read_b64 v[224:225], v180 offset:35424
	ds_read_b64 v[226:227], v180 offset:39744
	ds_read_b64 v[228:229], v180 offset:39776
	v_mfma_f32_16x16x32_bf16 v[68:71], v[152:155], v[136:139], v[68:71]
	v_exp_f32_e32 v88, v88
	v_exp_f32_e32 v89, v89
	v_mfma_f32_16x16x32_bf16 v[56:59], v[152:155], v[140:143], v[56:59]
	v_exp_f32_e32 v90, v90
	v_exp_f32_e32 v91, v91
	s_waitcnt lgkmcnt(8)
	v_mfma_f32_16x16x32_bf16 v[32:35], v[198:201], v[136:139], v[32:35]
	v_exp_f32_e32 v96, v96
	v_exp_f32_e32 v97, v97
	v_mfma_f32_16x16x32_bf16 v[36:39], v[198:201], v[140:143], v[36:39]
	v_exp_f32_e32 v98, v98
	v_exp_f32_e32 v99, v99
	v_exp_f32_e32 v92, v92
	v_mfma_f32_16x16x32_bf16 v[40:43], v[202:205], v[136:139], v[40:43]
	v_exp_f32_e32 v93, v93
	v_exp_f32_e32 v94, v94
	v_mfma_f32_16x16x32_bf16 v[60:63], v[202:205], v[140:143], v[60:63]
	v_exp_f32_e32 v95, v95
	v_exp_f32_e32 v100, v100
	v_exp_f32_e32 v101, v101
	v_mfma_f32_16x16x32_bf16 v[44:47], v[206:209], v[136:139], v[44:47]
	v_exp_f32_e32 v102, v102
	v_exp_f32_e32 v103, v103
	v_mfma_f32_16x16x32_bf16 v[64:67], v[206:209], v[140:143], v[64:67]
	v_cvt_pk_bf16_f32 v144, v88, v89
	v_cvt_pk_bf16_f32 v145, v90, v91
	v_cvt_pk_bf16_f32 v146, v96, v97
	v_mfma_f32_16x16x32_bf16 v[48:51], v[210:213], v[136:139], v[48:51]
	v_cvt_pk_bf16_f32 v147, v98, v99
	v_cvt_pk_bf16_f32 v148, v92, v93
	v_mfma_f32_16x16x32_bf16 v[52:55], v[210:213], v[140:143], v[52:55]
	v_cvt_pk_bf16_f32 v149, v94, v95
	v_cvt_pk_bf16_f32 v150, v100, v101
	v_cvt_pk_bf16_f32 v151, v102, v103
	ds_read_b64 v[198:199], v180 offset:26752
	ds_read_b64 v[200:201], v180 offset:26784
	ds_read_b64 v[202:203], v180 offset:31104
	ds_read_b64 v[204:205], v180 offset:31136
	ds_read_b64 v[206:207], v180 offset:35456
	ds_read_b64 v[208:209], v180 offset:35488
	ds_read_b64 v[210:211], v180 offset:39808
	ds_read_b64 v[212:213], v180 offset:39840
	s_nop 1
	v_mfma_f32_16x16x32_bf16 v[68:71], v[152:155], v[144:147], v[68:71]
	v_exp_f32_e32 v104, v104
	v_exp_f32_e32 v105, v105
	v_mfma_f32_16x16x32_bf16 v[56:59], v[152:155], v[148:151], v[56:59]
	v_exp_f32_e32 v106, v106
	v_exp_f32_e32 v107, v107
	s_waitcnt lgkmcnt(8)
	v_mfma_f32_16x16x32_bf16 v[32:35], v[214:217], v[144:147], v[32:35]
	v_exp_f32_e32 v112, v112
	v_exp_f32_e32 v113, v113
	v_mfma_f32_16x16x32_bf16 v[36:39], v[214:217], v[148:151], v[36:39]
	v_exp_f32_e32 v114, v114
	v_exp_f32_e32 v115, v115
	v_exp_f32_e32 v108, v108
	v_mfma_f32_16x16x32_bf16 v[40:43], v[218:221], v[144:147], v[40:43]
	v_exp_f32_e32 v109, v109
	v_exp_f32_e32 v110, v110
	v_mfma_f32_16x16x32_bf16 v[60:63], v[218:221], v[148:151], v[60:63]
	v_exp_f32_e32 v111, v111
	v_exp_f32_e32 v116, v116
	v_exp_f32_e32 v117, v117
	v_mfma_f32_16x16x32_bf16 v[44:47], v[222:225], v[144:147], v[44:47]
	v_exp_f32_e32 v118, v118
	v_exp_f32_e32 v119, v119
	v_mfma_f32_16x16x32_bf16 v[64:67], v[222:225], v[148:151], v[64:67]
	v_cvt_pk_bf16_f32 v136, v104, v105
	v_cvt_pk_bf16_f32 v137, v106, v107
	v_cvt_pk_bf16_f32 v138, v112, v113
	v_mfma_f32_16x16x32_bf16 v[48:51], v[226:229], v[144:147], v[48:51]
	v_cvt_pk_bf16_f32 v139, v114, v115
	v_cvt_pk_bf16_f32 v140, v108, v109
	v_mfma_f32_16x16x32_bf16 v[52:55], v[226:229], v[148:151], v[52:55]
	v_cvt_pk_bf16_f32 v141, v110, v111
	v_cvt_pk_bf16_f32 v142, v116, v117
	v_cvt_pk_bf16_f32 v143, v118, v119
	ds_read_b64 v[214:215], v180 offset:26816
	ds_read_b64 v[216:217], v180 offset:26848
	ds_read_b64 v[218:219], v180 offset:31168
	ds_read_b64 v[220:221], v180 offset:31200
	ds_read_b64 v[222:223], v180 offset:35520
	ds_read_b64 v[224:225], v180 offset:35552
	ds_read_b64 v[226:227], v180 offset:39872
	ds_read_b64 v[228:229], v180 offset:39904
	s_nop 1
	v_mfma_f32_16x16x32_bf16 v[68:71], v[152:155], v[136:139], v[68:71]
	v_exp_f32_e32 v120, v120
	v_exp_f32_e32 v121, v121
	v_mfma_f32_16x16x32_bf16 v[56:59], v[152:155], v[140:143], v[56:59]
	v_exp_f32_e32 v122, v122
	v_exp_f32_e32 v123, v123
	s_waitcnt lgkmcnt(8)
; DEV float ex2(float x) { return __builtin_amdgcn_exp2f(x); }
; DEV void attn_item(const Params& p, int bl, int head, int q0, int nkeys, char* smem, int tid) {
;     ...
;     for (int hh = 0; hh < 2; ++hh) {
;       f32x4 s[4][2];
; #pragma unroll
;       for (int kf = 0; kf < 4; ++kf) {
; #pragma unroll
;         for (int ks = 0; ks < 3; ++ks) {
;           bf16x8 a = *(const bf16x8*)(kb + (hh * 64 + kf * 16 + fr) * KROW + ks * 64 + fq * 16);
;           s[kf][0] = __builtin_amdgcn_mfma_f32_16x16x32_bf16(a, qf[0][ks], ks == 0 ? negm[0] : s[kf][0], 0, 0, 0);
;           s[kf][1] = __builtin_amdgcn_mfma_f32_16x16x32_bf16(a, qf[1][ks], ks == 0 ? negm[1] : s[kf][1], 0, 0, 0);
;         }
;       }
; #pragma unroll
;       for (int kk = 0; kk < 2; ++kk) {
;         bf16x8 pb[2];
; #pragma unroll
;         for (int qt = 0; qt < 2; ++qt) {
;           const float e0 = ex2(s[2 * kk][qt][0]), e1 = ex2(s[2 * kk][qt][1]), e2 = ex2(s[2 * kk][qt][2]), e3 = ex2(s[2 * kk][qt][3]);
;           const float e4 = ex2(s[2 * kk + 1][qt][0]), e5 = ex2(s[2 * kk + 1][qt][1]), e6 = ex2(s[2 * kk + 1][qt][2]), e7 = ex2(s[2 * kk + 1][qt][3]);
;           u32x4 cw = {pack2(e0, e1), pack2(e2, e3), pack2(e4, e5), pack2(e6, e7)};
;           pb[qt] = __builtin_bit_cast(bf16x8, cw);
;         }
;         lacc[0] = __builtin_amdgcn_mfma_f32_16x16x32_bf16(ones, pb[0], lacc[0], 0, 0, 0);
;         lacc[1] = __builtin_amdgcn_mfma_f32_16x16x32_bf16(ones, pb[1], lacc[1], 0, 0, 0);
; #pragma unroll
;         for (int dvf = 0; dvf < 4; ++dvf) {
;           const char* vp = vb + (dvf * 16 + fr) * VROW + (hh * 64 + kk * 32 + fq * 4) * 2;
;           const uint2 h0 = *(const uint2*)vp, h1 = *(const uint2*)(vp + 32);
;           u32x4 vw = {h0.x, h0.y, h1.x, h1.y};
;           const bf16x8 va = __builtin_bit_cast(bf16x8, vw);
;           o[dvf][0] = __builtin_amdgcn_mfma_f32_16x16x32_bf16(va, pb[0], o[dvf][0], 0, 0, 0);
;           o[dvf][1] = __builtin_amdgcn_mfma_f32_16x16x32_bf16(va, pb[1], o[dvf][1], 0, 0, 0);
;         }
;       }
;     }
;     if (t + 1 < nt) {
;       char* nb = smem + ((t + 1) & 1) * ASTG;
; #pragma unroll
;       for (int i = 0; i < 3; ++i) *(u32x4*)(nb + koff[i]) = kr[i];
; #pragma unroll
;       for (int i = 0; i < 2; ++i) *(u32x4*)(nb + KBYTES + voffl[i]) = vr[i];
;     }
	v_mfma_f32_16x16x32_bf16 v[32:35], v[198:201], v[136:139], v[32:35]
	v_exp_f32_e32 v128, v128
	v_exp_f32_e32 v129, v129
	v_mfma_f32_16x16x32_bf16 v[36:39], v[198:201], v[140:143], v[36:39]
	v_exp_f32_e32 v130, v130
	v_exp_f32_e32 v131, v131
	v_exp_f32_e32 v124, v124
	v_mfma_f32_16x16x32_bf16 v[40:43], v[202:205], v[136:139], v[40:43]
	v_exp_f32_e32 v125, v125
	v_exp_f32_e32 v126, v126
	v_mfma_f32_16x16x32_bf16 v[60:63], v[202:205], v[140:143], v[60:63]
	v_exp_f32_e32 v127, v127
	v_exp_f32_e32 v132, v132
	v_exp_f32_e32 v133, v133
	v_mfma_f32_16x16x32_bf16 v[44:47], v[206:209], v[136:139], v[44:47]
	v_exp_f32_e32 v134, v134
	v_exp_f32_e32 v135, v135
	v_mfma_f32_16x16x32_bf16 v[64:67], v[206:209], v[140:143], v[64:67]
	v_cvt_pk_bf16_f32 v144, v120, v121
	v_cvt_pk_bf16_f32 v145, v122, v123
	v_cvt_pk_bf16_f32 v146, v128, v129
	v_mfma_f32_16x16x32_bf16 v[48:51], v[210:213], v[136:139], v[48:51]
	v_cvt_pk_bf16_f32 v147, v130, v131
	v_cvt_pk_bf16_f32 v148, v124, v125
	v_mfma_f32_16x16x32_bf16 v[52:55], v[210:213], v[140:143], v[52:55]
	v_cvt_pk_bf16_f32 v149, v126, v127
	v_cvt_pk_bf16_f32 v150, v132, v133
	v_cvt_pk_bf16_f32 v151, v134, v135
	s_nop 1
	v_mfma_f32_16x16x32_bf16 v[68:71], v[152:155], v[144:147], v[68:71]
	v_mfma_f32_16x16x32_bf16 v[56:59], v[152:155], v[148:151], v[56:59]
	s_waitcnt lgkmcnt(0)
	v_mfma_f32_16x16x32_bf16 v[32:35], v[214:217], v[144:147], v[32:35]
	v_mfma_f32_16x16x32_bf16 v[36:39], v[214:217], v[148:151], v[36:39]
	v_mfma_f32_16x16x32_bf16 v[40:43], v[218:221], v[144:147], v[40:43]
	v_mfma_f32_16x16x32_bf16 v[60:63], v[218:221], v[148:151], v[60:63]
	v_mfma_f32_16x16x32_bf16 v[44:47], v[222:225], v[144:147], v[44:47]
	v_mfma_f32_16x16x32_bf16 v[64:67], v[222:225], v[148:151], v[64:67]
	v_mfma_f32_16x16x32_bf16 v[48:51], v[226:229], v[144:147], v[48:51]
	v_mfma_f32_16x16x32_bf16 v[52:55], v[226:229], v[148:151], v[52:55]
	s_waitcnt vmcnt(0)
	ds_write_b128 v184, v[238:241]
	ds_write_b128 v185, v[242:245]
	ds_write_b128 v186, v[246:249]
	ds_write_b128 v187, v[230:233] offset:28672
	ds_write_b128 v188, v[234:237] offset:28672
	v_add3_u32 v179, s12, v156, v181
	ds_read_b128 v[198:201], v179
	ds_read_b128 v[202:205], v179 offset:3584
	ds_read_b128 v[206:209], v179 offset:7168
	ds_read_b128 v[210:213], v179 offset:10752
	ds_read_b128 v[214:217], v179 offset:64
	ds_read_b128 v[218:221], v179 offset:3648
	ds_read_b128 v[222:225], v179 offset:7232
	ds_read_b128 v[226:229], v179 offset:10816
	s_waitcnt lgkmcnt(7)
	v_mfma_f32_16x16x32_bf16 v[72:75], v[198:201], v[12:15], v[24:27]
	v_mfma_f32_16x16x32_bf16 v[76:79], v[198:201], v[20:23], v[28:31]
	ds_read_b128 v[198:201], v179 offset:128
	s_waitcnt lgkmcnt(7)
	v_mfma_f32_16x16x32_bf16 v[80:83], v[202:205], v[12:15], v[24:27]
	v_mfma_f32_16x16x32_bf16 v[84:87], v[202:205], v[20:23], v[28:31]
	ds_read_b128 v[202:205], v179 offset:3712
	s_waitcnt lgkmcnt(7)
	v_mfma_f32_16x16x32_bf16 v[88:91], v[206:209], v[12:15], v[24:27]
	v_mfma_f32_16x16x32_bf16 v[92:95], v[206:209], v[20:23], v[28:31]
	ds_read_b128 v[206:209], v179 offset:7296
	s_waitcnt lgkmcnt(7)
	v_mfma_f32_16x16x32_bf16 v[96:99], v[210:213], v[12:15], v[24:27]
	v_mfma_f32_16x16x32_bf16 v[100:103], v[210:213], v[20:23], v[28:31]
	ds_read_b128 v[210:213], v179 offset:10880
	s_waitcnt lgkmcnt(7)
	v_mfma_f32_16x16x32_bf16 v[72:75], v[214:217], v[8:11], v[72:75]
	v_mfma_f32_16x16x32_bf16 v[76:79], v[214:217], v[16:19], v[76:79]
	ds_read_b128 v[214:217], v179 offset:14336
	s_waitcnt lgkmcnt(7)
	v_mfma_f32_16x16x32_bf16 v[80:83], v[218:221], v[8:11], v[80:83]
	v_mfma_f32_16x16x32_bf16 v[84:87], v[218:221], v[16:19], v[84:87]
	ds_read_b128 v[218:221], v179 offset:17920
	s_waitcnt lgkmcnt(7)
	v_mfma_f32_16x16x32_bf16 v[88:91], v[222:225], v[8:11], v[88:91]
	v_mfma_f32_16x16x32_bf16 v[92:95], v[222:225], v[16:19], v[92:95]
	ds_read_b128 v[222:225], v179 offset:21504
	s_waitcnt lgkmcnt(7)
	v_mfma_f32_16x16x32_bf16 v[96:99], v[226:229], v[8:11], v[96:99]
	v_mfma_f32_16x16x32_bf16 v[100:103], v[226:229], v[16:19], v[100:103]
	ds_read_b128 v[226:229], v179 offset:25088
	s_waitcnt lgkmcnt(7)
	v_mfma_f32_16x16x32_bf16 v[72:75], v[198:201], v[4:7], v[72:75]
	v_mfma_f32_16x16x32_bf16 v[76:79], v[198:201], v[0:3], v[76:79]
	ds_read_b128 v[198:201], v179 offset:14400
	s_waitcnt lgkmcnt(7)
	v_mfma_f32_16x16x32_bf16 v[80:83], v[202:205], v[4:7], v[80:83]
	v_mfma_f32_16x16x32_bf16 v[84:87], v[202:205], v[0:3], v[84:87]
	ds_read_b128 v[202:205], v179 offset:17984
	s_waitcnt lgkmcnt(7)
	v_mfma_f32_16x16x32_bf16 v[88:91], v[206:209], v[4:7], v[88:91]
	v_mfma_f32_16x16x32_bf16 v[92:95], v[206:209], v[0:3], v[92:95]
	ds_read_b128 v[206:209], v179 offset:21568
	s_waitcnt lgkmcnt(7)
	v_mfma_f32_16x16x32_bf16 v[96:99], v[210:213], v[4:7], v[96:99]
	v_mfma_f32_16x16x32_bf16 v[100:103], v[210:213], v[0:3], v[100:103]
	ds_read_b128 v[210:213], v179 offset:25152
	s_waitcnt lgkmcnt(7)
	v_mfma_f32_16x16x32_bf16 v[104:107], v[214:217], v[12:15], v[24:27]
	v_mfma_f32_16x16x32_bf16 v[108:111], v[214:217], v[20:23], v[28:31]
	ds_read_b128 v[214:217], v179 offset:14464
	s_waitcnt lgkmcnt(7)
	v_mfma_f32_16x16x32_bf16 v[112:115], v[218:221], v[12:15], v[24:27]
	v_mfma_f32_16x16x32_bf16 v[116:119], v[218:221], v[20:23], v[28:31]
	ds_read_b128 v[218:221], v179 offset:18048
	s_waitcnt lgkmcnt(7)
	v_mfma_f32_16x16x32_bf16 v[120:123], v[222:225], v[12:15], v[24:27]
	v_exp_f32_e32 v72, v72
	v_mfma_f32_16x16x32_bf16 v[124:127], v[222:225], v[20:23], v[28:31]
	v_exp_f32_e32 v73, v73
	ds_read_b128 v[222:225], v179 offset:21632
	s_waitcnt lgkmcnt(7)
	v_mfma_f32_16x16x32_bf16 v[128:131], v[226:229], v[12:15], v[24:27]
	v_exp_f32_e32 v74, v74
	v_mfma_f32_16x16x32_bf16 v[132:135], v[226:229], v[20:23], v[28:31]
	v_exp_f32_e32 v75, v75
	ds_read_b128 v[226:229], v179 offset:25216
	s_waitcnt lgkmcnt(7)
; DEV void attn_item(const Params& p, int bl, int head, int q0, int nkeys, char* smem, int tid) {
;     ...
;   for (int t = 0; t < nt; ++t) {
;     if (t + 1 < nt) {
; #pragma unroll
;       for (int i = 0; i < 3; ++i) kr[i] = *(const u32x4*)(Kg + (long)(t + 1) * 128 * 96 + (long)(i * 512 + tid) * 8);
; #pragma unroll
;       for (int i = 0; i < 2; ++i) vr[i] = *(const u32x4*)(Vg + (t + 1) * 128 + voffg[i]);
;     }
;     const char* kb = smem + (t & 1) * ASTG;
;     const char* vb = kb + KBYTES;
; #pragma unroll
;     for (int hh = 0; hh < 2; ++hh) {
;       f32x4 s[4][2];
; #pragma unroll
;       for (int kf = 0; kf < 4; ++kf) {
; #pragma unroll
;         for (int ks = 0; ks < 3; ++ks) {
;           bf16x8 a = *(const bf16x8*)(kb + (hh * 64 + kf * 16 + fr) * KROW + ks * 64 + fq * 16);
;           s[kf][0] = __builtin_amdgcn_mfma_f32_16x16x32_bf16(a, qf[0][ks], ks == 0 ? negm[0] : s[kf][0], 0, 0, 0);
;           s[kf][1] = __builtin_amdgcn_mfma_f32_16x16x32_bf16(a, qf[1][ks], ks == 0 ? negm[1] : s[kf][1], 0, 0, 0);
;         }
;       }
; #pragma unroll
;       for (int kk = 0; kk < 2; ++kk) {
;         bf16x8 pb[2];
; #pragma unroll
;         for (int qt = 0; qt < 2; ++qt) {
;           const float e0 = ex2(s[2 * kk][qt][0]), e1 = ex2(s[2 * kk][qt][1]), e2 = ex2(s[2 * kk][qt][2]), e3 = ex2(s[2 * kk][qt][3]);
;           const float e4 = ex2(s[2 * kk + 1][qt][0]), e5 = ex2(s[2 * kk + 1][qt][1]), e6 = ex2(s[2 * kk + 1][qt][2]), e7 = ex2(s[2 * kk + 1][qt][3]);
;           u32x4 cw = {pack2(e0, e1), pack2(e2, e3), pack2(e4, e5), pack2(e6, e7)};
;           pb[qt] = __builtin_bit_cast(bf16x8, cw);
;         }
;         lacc[0] = __builtin_amdgcn_mfma_f32_16x16x32_bf16(ones, pb[0], lacc[0], 0, 0, 0);
;         lacc[1] = __builtin_amdgcn_mfma_f32_16x16x32_bf16(ones, pb[1], lacc[1], 0, 0, 0);
; #pragma unroll
;         for (int dvf = 0; dvf < 4; ++dvf) {
;           const char* vp = vb + (dvf * 16 + fr) * VROW + (hh * 64 + kk * 32 + fq * 4) * 2;
;           const uint2 h0 = *(const uint2*)vp, h1 = *(const uint2*)(vp + 32);
;           u32x4 vw = {h0.x, h0.y, h1.x, h1.y};
;           const bf16x8 va = __builtin_bit_cast(bf16x8, vw);
;           o[dvf][0] = __builtin_amdgcn_mfma_f32_16x16x32_bf16(va, pb[0], o[dvf][0], 0, 0, 0);
;           o[dvf][1] = __builtin_amdgcn_mfma_f32_16x16x32_bf16(va, pb[1], o[dvf][1], 0, 0, 0);
;         }
	v_mfma_f32_16x16x32_bf16 v[104:107], v[198:201], v[8:11], v[104:107]
	v_exp_f32_e32 v80, v80
	v_exp_f32_e32 v81, v81
	v_mfma_f32_16x16x32_bf16 v[108:111], v[198:201], v[16:19], v[108:111]
	v_exp_f32_e32 v82, v82
	s_waitcnt lgkmcnt(6)
	v_mfma_f32_16x16x32_bf16 v[112:115], v[202:205], v[8:11], v[112:115]
	v_exp_f32_e32 v83, v83
	v_mfma_f32_16x16x32_bf16 v[116:119], v[202:205], v[16:19], v[116:119]
	v_exp_f32_e32 v76, v76
	s_waitcnt lgkmcnt(5)
	v_mfma_f32_16x16x32_bf16 v[120:123], v[206:209], v[8:11], v[120:123]
	v_exp_f32_e32 v77, v77
	v_mfma_f32_16x16x32_bf16 v[124:127], v[206:209], v[16:19], v[124:127]
	v_exp_f32_e32 v78, v78
	v_exp_f32_e32 v79, v79
	s_waitcnt lgkmcnt(4)
	v_mfma_f32_16x16x32_bf16 v[128:131], v[210:213], v[8:11], v[128:131]
	v_exp_f32_e32 v84, v84
	v_mfma_f32_16x16x32_bf16 v[132:135], v[210:213], v[16:19], v[132:135]
	v_exp_f32_e32 v85, v85
	s_waitcnt lgkmcnt(3)
	v_mfma_f32_16x16x32_bf16 v[104:107], v[214:217], v[4:7], v[104:107]
	v_exp_f32_e32 v86, v86
	v_mfma_f32_16x16x32_bf16 v[108:111], v[214:217], v[0:3], v[108:111]
	v_exp_f32_e32 v87, v87
	s_waitcnt lgkmcnt(2)
	v_mfma_f32_16x16x32_bf16 v[112:115], v[218:221], v[4:7], v[112:115]
	v_cvt_pk_bf16_f32 v136, v72, v73
	v_cvt_pk_bf16_f32 v137, v74, v75
	v_mfma_f32_16x16x32_bf16 v[116:119], v[218:221], v[0:3], v[116:119]
	v_cvt_pk_bf16_f32 v138, v80, v81
	s_waitcnt lgkmcnt(1)
	v_mfma_f32_16x16x32_bf16 v[120:123], v[222:225], v[4:7], v[120:123]
	v_cvt_pk_bf16_f32 v139, v82, v83
	v_mfma_f32_16x16x32_bf16 v[124:127], v[222:225], v[0:3], v[124:127]
	v_cvt_pk_bf16_f32 v140, v76, v77
	s_waitcnt lgkmcnt(0)
	v_mfma_f32_16x16x32_bf16 v[128:131], v[226:229], v[4:7], v[128:131]
	v_cvt_pk_bf16_f32 v141, v78, v79
	v_mfma_f32_16x16x32_bf16 v[132:135], v[226:229], v[0:3], v[132:135]
	v_cvt_pk_bf16_f32 v142, v84, v85
	v_cvt_pk_bf16_f32 v143, v86, v87
	s_waitcnt lgkmcnt(0)
	s_barrier
	s_mov_b32 s18, s15
	s_mov_b32 s15, s12
	s_mov_b32 s12, s9
	s_mov_b32 s9, s18
	s_add_i32 s13, s13, 1
.Lattn_b_loop:
	global_load_dwordx4 v[230:233], v[164:165], off
	global_load_dwordx4 v[234:237], v[166:167], off
	global_load_dwordx4 v[238:241], v[168:169], off
	global_load_dwordx4 v[242:245], v[170:171], off
	global_load_dwordx4 v[246:249], v[172:173], off
	v_lshl_add_u64 v[164:165], v[164:165], 0, s[26:27]
	v_lshl_add_u64 v[166:167], v[166:167], 0, s[26:27]
	v_lshl_add_u64 v[168:169], v[168:169], 0, s[16:17]
	v_lshl_add_u64 v[170:171], v[170:171], 0, s[16:17]
	v_lshl_add_u64 v[172:173], v[172:173], 0, s[16:17]
	v_add_u32_e32 v184, s9, v190
	v_add_u32_e32 v185, s9, v191
	v_add_u32_e32 v186, s9, v192
	v_add_u32_e32 v187, s9, v160
	v_add_u32_e32 v188, s9, v162
	v_add3_u32 v180, s15, v176, v177
	ds_read_b64 v[198:199], v180 offset:28672
	ds_read_b64 v[200:201], v180 offset:28704
	ds_read_b64 v[202:203], v180 offset:33024
	ds_read_b64 v[204:205], v180 offset:33056
	ds_read_b64 v[206:207], v180 offset:37376
	ds_read_b64 v[208:209], v180 offset:37408
	ds_read_b64 v[210:211], v180 offset:41728
	ds_read_b64 v[212:213], v180 offset:41760
	ds_read_b64 v[214:215], v180 offset:28736
	ds_read_b64 v[216:217], v180 offset:28768
	ds_read_b64 v[218:219], v180 offset:33088
	ds_read_b64 v[220:221], v180 offset:33120
	ds_read_b64 v[222:223], v180 offset:37440
	ds_read_b64 v[224:225], v180 offset:37472
	ds_read_b64 v[226:227], v180 offset:41792
	ds_read_b64 v[228:229], v180 offset:41824
	v_mfma_f32_16x16x32_bf16 v[68:71], v[152:155], v[136:139], v[68:71]
	v_exp_f32_e32 v88, v88
	v_exp_f32_e32 v89, v89
	v_mfma_f32_16x16x32_bf16 v[56:59], v[152:155], v[140:143], v[56:59]
	v_exp_f32_e32 v90, v90
	v_exp_f32_e32 v91, v91
	s_waitcnt lgkmcnt(8)
	v_mfma_f32_16x16x32_bf16 v[32:35], v[198:201], v[136:139], v[32:35]
	v_exp_f32_e32 v96, v96
	v_exp_f32_e32 v97, v97
	v_mfma_f32_16x16x32_bf16 v[36:39], v[198:201], v[140:143], v[36:39]
	v_exp_f32_e32 v98, v98
	v_exp_f32_e32 v99, v99
	v_exp_f32_e32 v92, v92
	v_mfma_f32_16x16x32_bf16 v[40:43], v[202:205], v[136:139], v[40:43]
	v_exp_f32_e32 v93, v93
	v_exp_f32_e32 v94, v94
	v_mfma_f32_16x16x32_bf16 v[60:63], v[202:205], v[140:143], v[60:63]
	v_exp_f32_e32 v95, v95
	v_exp_f32_e32 v100, v100
	v_exp_f32_e32 v101, v101
	v_mfma_f32_16x16x32_bf16 v[44:47], v[206:209], v[136:139], v[44:47]
	v_exp_f32_e32 v102, v102
	v_exp_f32_e32 v103, v103
	v_mfma_f32_16x16x32_bf16 v[64:67], v[206:209], v[140:143], v[64:67]
	v_cvt_pk_bf16_f32 v144, v88, v89
	v_cvt_pk_bf16_f32 v145, v90, v91
	v_cvt_pk_bf16_f32 v146, v96, v97
	v_mfma_f32_16x16x32_bf16 v[48:51], v[210:213], v[136:139], v[48:51]
	v_cvt_pk_bf16_f32 v147, v98, v99
	v_cvt_pk_bf16_f32 v148, v92, v93
	v_mfma_f32_16x16x32_bf16 v[52:55], v[210:213], v[140:143], v[52:55]
	v_cvt_pk_bf16_f32 v149, v94, v95
	v_cvt_pk_bf16_f32 v150, v100, v101
	v_cvt_pk_bf16_f32 v151, v102, v103
	ds_read_b64 v[198:199], v180 offset:28800
	ds_read_b64 v[200:201], v180 offset:28832
	ds_read_b64 v[202:203], v180 offset:33152
	ds_read_b64 v[204:205], v180 offset:33184
	ds_read_b64 v[206:207], v180 offset:37504
	ds_read_b64 v[208:209], v180 offset:37536
	ds_read_b64 v[210:211], v180 offset:41856
	ds_read_b64 v[212:213], v180 offset:41888
	s_nop 1
	v_mfma_f32_16x16x32_bf16 v[68:71], v[152:155], v[144:147], v[68:71]
	v_exp_f32_e32 v104, v104
	v_exp_f32_e32 v105, v105
	v_mfma_f32_16x16x32_bf16 v[56:59], v[152:155], v[148:151], v[56:59]
	v_exp_f32_e32 v106, v106
	v_exp_f32_e32 v107, v107
	s_waitcnt lgkmcnt(8)
; DEV void attn_item(const Params& p, int bl, int head, int q0, int nkeys, char* smem, int tid) {
;     ...
;   for (int t = 0; t < nt; ++t) {
;     if (t + 1 < nt) {
; #pragma unroll
;       for (int i = 0; i < 3; ++i) kr[i] = *(const u32x4*)(Kg + (long)(t + 1) * 128 * 96 + (long)(i * 512 + tid) * 8);
; #pragma unroll
;       for (int i = 0; i < 2; ++i) vr[i] = *(const u32x4*)(Vg + (t + 1) * 128 + voffg[i]);
;     }
;     const char* kb = smem + (t & 1) * ASTG;
;     const char* vb = kb + KBYTES;
; #pragma unroll
;     for (int hh = 0; hh < 2; ++hh) {
;       f32x4 s[4][2];
; #pragma unroll
;       for (int kf = 0; kf < 4; ++kf) {
; #pragma unroll
;         for (int ks = 0; ks < 3; ++ks) {
;           bf16x8 a = *(const bf16x8*)(kb + (hh * 64 + kf * 16 + fr) * KROW + ks * 64 + fq * 16);
;           s[kf][0] = __builtin_amdgcn_mfma_f32_16x16x32_bf16(a, qf[0][ks], ks == 0 ? negm[0] : s[kf][0], 0, 0, 0);
;           s[kf][1] = __builtin_amdgcn_mfma_f32_16x16x32_bf16(a, qf[1][ks], ks == 0 ? negm[1] : s[kf][1], 0, 0, 0);
;         }
;       }
; #pragma unroll
;       for (int kk = 0; kk < 2; ++kk) {
;         bf16x8 pb[2];
; #pragma unroll
;         for (int qt = 0; qt < 2; ++qt) {
;           const float e0 = ex2(s[2 * kk][qt][0]), e1 = ex2(s[2 * kk][qt][1]), e2 = ex2(s[2 * kk][qt][2]), e3 = ex2(s[2 * kk][qt][3]);
;           const float e4 = ex2(s[2 * kk + 1][qt][0]), e5 = ex2(s[2 * kk + 1][qt][1]), e6 = ex2(s[2 * kk + 1][qt][2]), e7 = ex2(s[2 * kk + 1][qt][3]);
;           u32x4 cw = {pack2(e0, e1), pack2(e2, e3), pack2(e4, e5), pack2(e6, e7)};
;           pb[qt] = __builtin_bit_cast(bf16x8, cw);
;         }
;         lacc[0] = __builtin_amdgcn_mfma_f32_16x16x32_bf16(ones, pb[0], lacc[0], 0, 0, 0);
;         lacc[1] = __builtin_amdgcn_mfma_f32_16x16x32_bf16(ones, pb[1], lacc[1], 0, 0, 0);
; #pragma unroll
;         for (int dvf = 0; dvf < 4; ++dvf) {
;           const char* vp = vb + (dvf * 16 + fr) * VROW + (hh * 64 + kk * 32 + fq * 4) * 2;
;           const uint2 h0 = *(const uint2*)vp, h1 = *(const uint2*)(vp + 32);
;           u32x4 vw = {h0.x, h0.y, h1.x, h1.y};
;           const bf16x8 va = __builtin_bit_cast(bf16x8, vw);
;           o[dvf][0] = __builtin_amdgcn_mfma_f32_16x16x32_bf16(va, pb[0], o[dvf][0], 0, 0, 0);
;           o[dvf][1] = __builtin_amdgcn_mfma_f32_16x16x32_bf16(va, pb[1], o[dvf][1], 0, 0, 0);
;         }
;       }
;     }
	v_mfma_f32_16x16x32_bf16 v[32:35], v[214:217], v[144:147], v[32:35]
	v_exp_f32_e32 v112, v112
	v_exp_f32_e32 v113, v113
	v_mfma_f32_16x16x32_bf16 v[36:39], v[214:217], v[148:151], v[36:39]
	v_exp_f32_e32 v114, v114
	v_exp_f32_e32 v115, v115
	v_exp_f32_e32 v108, v108
	v_mfma_f32_16x16x32_bf16 v[40:43], v[218:221], v[144:147], v[40:43]
	v_exp_f32_e32 v109, v109
	v_exp_f32_e32 v110, v110
	v_mfma_f32_16x16x32_bf16 v[60:63], v[218:221], v[148:151], v[60:63]
	v_exp_f32_e32 v111, v111
	v_exp_f32_e32 v116, v116
	v_exp_f32_e32 v117, v117
	v_mfma_f32_16x16x32_bf16 v[44:47], v[222:225], v[144:147], v[44:47]
	v_exp_f32_e32 v118, v118
	v_exp_f32_e32 v119, v119
	v_mfma_f32_16x16x32_bf16 v[64:67], v[222:225], v[148:151], v[64:67]
	v_cvt_pk_bf16_f32 v136, v104, v105
	v_cvt_pk_bf16_f32 v137, v106, v107
	v_cvt_pk_bf16_f32 v138, v112, v113
	v_mfma_f32_16x16x32_bf16 v[48:51], v[226:229], v[144:147], v[48:51]
	v_cvt_pk_bf16_f32 v139, v114, v115
	v_cvt_pk_bf16_f32 v140, v108, v109
	v_mfma_f32_16x16x32_bf16 v[52:55], v[226:229], v[148:151], v[52:55]
	v_cvt_pk_bf16_f32 v141, v110, v111
	v_cvt_pk_bf16_f32 v142, v116, v117
	v_cvt_pk_bf16_f32 v143, v118, v119
	ds_read_b64 v[214:215], v180 offset:28864
	ds_read_b64 v[216:217], v180 offset:28896
	ds_read_b64 v[218:219], v180 offset:33216
	ds_read_b64 v[220:221], v180 offset:33248
	ds_read_b64 v[222:223], v180 offset:37568
	ds_read_b64 v[224:225], v180 offset:37600
	ds_read_b64 v[226:227], v180 offset:41920
	ds_read_b64 v[228:229], v180 offset:41952
	s_nop 1
	v_mfma_f32_16x16x32_bf16 v[68:71], v[152:155], v[136:139], v[68:71]
	v_exp_f32_e32 v120, v120
	v_exp_f32_e32 v121, v121
	v_mfma_f32_16x16x32_bf16 v[56:59], v[152:155], v[140:143], v[56:59]
	v_exp_f32_e32 v122, v122
	v_exp_f32_e32 v123, v123
	s_waitcnt lgkmcnt(8)
	v_mfma_f32_16x16x32_bf16 v[32:35], v[198:201], v[136:139], v[32:35]
	v_exp_f32_e32 v128, v128
	v_exp_f32_e32 v129, v129
	v_mfma_f32_16x16x32_bf16 v[36:39], v[198:201], v[140:143], v[36:39]
	v_exp_f32_e32 v130, v130
	v_exp_f32_e32 v131, v131
	v_exp_f32_e32 v124, v124
	v_mfma_f32_16x16x32_bf16 v[40:43], v[202:205], v[136:139], v[40:43]
	v_exp_f32_e32 v125, v125
	v_exp_f32_e32 v126, v126
	v_mfma_f32_16x16x32_bf16 v[60:63], v[202:205], v[140:143], v[60:63]
	v_exp_f32_e32 v127, v127
	v_exp_f32_e32 v132, v132
	v_exp_f32_e32 v133, v133
	v_mfma_f32_16x16x32_bf16 v[44:47], v[206:209], v[136:139], v[44:47]
	v_exp_f32_e32 v134, v134
	v_exp_f32_e32 v135, v135
	v_mfma_f32_16x16x32_bf16 v[64:67], v[206:209], v[140:143], v[64:67]
	v_cvt_pk_bf16_f32 v144, v120, v121
	v_cvt_pk_bf16_f32 v145, v122, v123
	v_cvt_pk_bf16_f32 v146, v128, v129
	v_mfma_f32_16x16x32_bf16 v[48:51], v[210:213], v[136:139], v[48:51]
	v_cvt_pk_bf16_f32 v147, v130, v131
	v_cvt_pk_bf16_f32 v148, v124, v125
	v_mfma_f32_16x16x32_bf16 v[52:55], v[210:213], v[140:143], v[52:55]
	v_cvt_pk_bf16_f32 v149, v126, v127
	v_cvt_pk_bf16_f32 v150, v132, v133
	v_cvt_pk_bf16_f32 v151, v134, v135
	s_nop 1
	v_mfma_f32_16x16x32_bf16 v[68:71], v[152:155], v[144:147], v[68:71]
	v_mfma_f32_16x16x32_bf16 v[56:59], v[152:155], v[148:151], v[56:59]
	s_waitcnt lgkmcnt(0)
	v_mfma_f32_16x16x32_bf16 v[32:35], v[214:217], v[144:147], v[32:35]
	v_mfma_f32_16x16x32_bf16 v[36:39], v[214:217], v[148:151], v[36:39]
	v_mfma_f32_16x16x32_bf16 v[40:43], v[218:221], v[144:147], v[40:43]
	v_mfma_f32_16x16x32_bf16 v[60:63], v[218:221], v[148:151], v[60:63]
	v_mfma_f32_16x16x32_bf16 v[44:47], v[222:225], v[144:147], v[44:47]
	v_mfma_f32_16x16x32_bf16 v[64:67], v[222:225], v[148:151], v[64:67]
	v_mfma_f32_16x16x32_bf16 v[48:51], v[226:229], v[144:147], v[48:51]
	v_mfma_f32_16x16x32_bf16 v[52:55], v[226:229], v[148:151], v[52:55]
	s_waitcnt vmcnt(0)
	ds_write_b128 v184, v[238:241]
	ds_write_b128 v185, v[242:245]
	ds_write_b128 v186, v[246:249]
	ds_write_b128 v187, v[230:233] offset:28672
	ds_write_b128 v188, v[234:237] offset:28672
	v_add3_u32 v179, s12, v156, v181
	ds_read_b128 v[198:201], v179
	ds_read_b128 v[202:205], v179 offset:3584
	ds_read_b128 v[206:209], v179 offset:7168
	ds_read_b128 v[210:213], v179 offset:10752
	ds_read_b128 v[214:217], v179 offset:64
	ds_read_b128 v[218:221], v179 offset:3648
	ds_read_b128 v[222:225], v179 offset:7232
	ds_read_b128 v[226:229], v179 offset:10816
	s_waitcnt lgkmcnt(7)
	v_mfma_f32_16x16x32_bf16 v[72:75], v[198:201], v[12:15], v[24:27]
	v_mfma_f32_16x16x32_bf16 v[76:79], v[198:201], v[20:23], v[28:31]
	ds_read_b128 v[198:201], v179 offset:128
	s_waitcnt lgkmcnt(7)
	v_mfma_f32_16x16x32_bf16 v[80:83], v[202:205], v[12:15], v[24:27]
	v_mfma_f32_16x16x32_bf16 v[84:87], v[202:205], v[20:23], v[28:31]
	ds_read_b128 v[202:205], v179 offset:3712
	s_waitcnt lgkmcnt(7)
	v_mfma_f32_16x16x32_bf16 v[88:91], v[206:209], v[12:15], v[24:27]
	v_mfma_f32_16x16x32_bf16 v[92:95], v[206:209], v[20:23], v[28:31]
	ds_read_b128 v[206:209], v179 offset:7296
	s_waitcnt lgkmcnt(7)
	v_mfma_f32_16x16x32_bf16 v[96:99], v[210:213], v[12:15], v[24:27]
	v_mfma_f32_16x16x32_bf16 v[100:103], v[210:213], v[20:23], v[28:31]
	ds_read_b128 v[210:213], v179 offset:10880
	s_waitcnt lgkmcnt(7)
	v_mfma_f32_16x16x32_bf16 v[72:75], v[214:217], v[8:11], v[72:75]
	v_mfma_f32_16x16x32_bf16 v[76:79], v[214:217], v[16:19], v[76:79]
	ds_read_b128 v[214:217], v179 offset:14336
	s_waitcnt lgkmcnt(7)
	v_mfma_f32_16x16x32_bf16 v[80:83], v[218:221], v[8:11], v[80:83]
	v_mfma_f32_16x16x32_bf16 v[84:87], v[218:221], v[16:19], v[84:87]
	ds_read_b128 v[218:221], v179 offset:17920
	s_waitcnt lgkmcnt(7)
	v_mfma_f32_16x16x32_bf16 v[88:91], v[222:225], v[8:11], v[88:91]
	v_mfma_f32_16x16x32_bf16 v[92:95], v[222:225], v[16:19], v[92:95]
	ds_read_b128 v[222:225], v179 offset:21504
	s_waitcnt lgkmcnt(7)
; DEV void attn_item(const Params& p, int bl, int head, int q0, int nkeys, char* smem, int tid) {
;     ...
;   for (int t = 0; t < nt; ++t) {
;     if (t + 1 < nt) {
; #pragma unroll
;       for (int i = 0; i < 3; ++i) kr[i] = *(const u32x4*)(Kg + (long)(t + 1) * 128 * 96 + (long)(i * 512 + tid) * 8);
; #pragma unroll
;       for (int i = 0; i < 2; ++i) vr[i] = *(const u32x4*)(Vg + (t + 1) * 128 + voffg[i]);
;     }
;     const char* kb = smem + (t & 1) * ASTG;
;     const char* vb = kb + KBYTES;
; #pragma unroll
;     for (int hh = 0; hh < 2; ++hh) {
;       f32x4 s[4][2];
; #pragma unroll
;       for (int kf = 0; kf < 4; ++kf) {
; #pragma unroll
;         for (int ks = 0; ks < 3; ++ks) {
;           bf16x8 a = *(const bf16x8*)(kb + (hh * 64 + kf * 16 + fr) * KROW + ks * 64 + fq * 16);
;           s[kf][0] = __builtin_amdgcn_mfma_f32_16x16x32_bf16(a, qf[0][ks], ks == 0 ? negm[0] : s[kf][0], 0, 0, 0);
;           s[kf][1] = __builtin_amdgcn_mfma_f32_16x16x32_bf16(a, qf[1][ks], ks == 0 ? negm[1] : s[kf][1], 0, 0, 0);
;         }
;       }
; #pragma unroll
;       for (int kk = 0; kk < 2; ++kk) {
;         bf16x8 pb[2];
; #pragma unroll
;         for (int qt = 0; qt < 2; ++qt) {
;           const float e0 = ex2(s[2 * kk][qt][0]), e1 = ex2(s[2 * kk][qt][1]), e2 = ex2(s[2 * kk][qt][2]), e3 = ex2(s[2 * kk][qt][3]);
;           const float e4 = ex2(s[2 * kk + 1][qt][0]), e5 = ex2(s[2 * kk + 1][qt][1]), e6 = ex2(s[2 * kk + 1][qt][2]), e7 = ex2(s[2 * kk + 1][qt][3]);
;           u32x4 cw = {pack2(e0, e1), pack2(e2, e3), pack2(e4, e5), pack2(e6, e7)};
;           pb[qt] = __builtin_bit_cast(bf16x8, cw);
;         }
;         lacc[0] = __builtin_amdgcn_mfma_f32_16x16x32_bf16(ones, pb[0], lacc[0], 0, 0, 0);
;         lacc[1] = __builtin_amdgcn_mfma_f32_16x16x32_bf16(ones, pb[1], lacc[1], 0, 0, 0);
; #pragma unroll
;         for (int dvf = 0; dvf < 4; ++dvf) {
;           const char* vp = vb + (dvf * 16 + fr) * VROW + (hh * 64 + kk * 32 + fq * 4) * 2;
;           const uint2 h0 = *(const uint2*)vp, h1 = *(const uint2*)(vp + 32);
;           u32x4 vw = {h0.x, h0.y, h1.x, h1.y};
;           const bf16x8 va = __builtin_bit_cast(bf16x8, vw);
;           o[dvf][0] = __builtin_amdgcn_mfma_f32_16x16x32_bf16(va, pb[0], o[dvf][0], 0, 0, 0);
;           o[dvf][1] = __builtin_amdgcn_mfma_f32_16x16x32_bf16(va, pb[1], o[dvf][1], 0, 0, 0);
;         }
;       }
;     }
	v_mfma_f32_16x16x32_bf16 v[96:99], v[226:229], v[8:11], v[96:99]
	v_mfma_f32_16x16x32_bf16 v[100:103], v[226:229], v[16:19], v[100:103]
	ds_read_b128 v[226:229], v179 offset:25088
	s_waitcnt lgkmcnt(7)
	v_mfma_f32_16x16x32_bf16 v[72:75], v[198:201], v[4:7], v[72:75]
	v_mfma_f32_16x16x32_bf16 v[76:79], v[198:201], v[0:3], v[76:79]
	ds_read_b128 v[198:201], v179 offset:14400
	s_waitcnt lgkmcnt(7)
	v_mfma_f32_16x16x32_bf16 v[80:83], v[202:205], v[4:7], v[80:83]
	v_mfma_f32_16x16x32_bf16 v[84:87], v[202:205], v[0:3], v[84:87]
	ds_read_b128 v[202:205], v179 offset:17984
	s_waitcnt lgkmcnt(7)
	v_mfma_f32_16x16x32_bf16 v[88:91], v[206:209], v[4:7], v[88:91]
	v_mfma_f32_16x16x32_bf16 v[92:95], v[206:209], v[0:3], v[92:95]
	ds_read_b128 v[206:209], v179 offset:21568
	s_waitcnt lgkmcnt(7)
	v_mfma_f32_16x16x32_bf16 v[96:99], v[210:213], v[4:7], v[96:99]
	v_mfma_f32_16x16x32_bf16 v[100:103], v[210:213], v[0:3], v[100:103]
	ds_read_b128 v[210:213], v179 offset:25152
	s_waitcnt lgkmcnt(7)
	v_mfma_f32_16x16x32_bf16 v[104:107], v[214:217], v[12:15], v[24:27]
	v_mfma_f32_16x16x32_bf16 v[108:111], v[214:217], v[20:23], v[28:31]
	ds_read_b128 v[214:217], v179 offset:14464
	s_waitcnt lgkmcnt(7)
	v_mfma_f32_16x16x32_bf16 v[112:115], v[218:221], v[12:15], v[24:27]
	v_mfma_f32_16x16x32_bf16 v[116:119], v[218:221], v[20:23], v[28:31]
	ds_read_b128 v[218:221], v179 offset:18048
	s_waitcnt lgkmcnt(7)
	v_mfma_f32_16x16x32_bf16 v[120:123], v[222:225], v[12:15], v[24:27]
	v_exp_f32_e32 v72, v72
	v_mfma_f32_16x16x32_bf16 v[124:127], v[222:225], v[20:23], v[28:31]
	v_exp_f32_e32 v73, v73
	ds_read_b128 v[222:225], v179 offset:21632
	s_waitcnt lgkmcnt(7)
	v_mfma_f32_16x16x32_bf16 v[128:131], v[226:229], v[12:15], v[24:27]
	v_exp_f32_e32 v74, v74
	v_mfma_f32_16x16x32_bf16 v[132:135], v[226:229], v[20:23], v[28:31]
	v_exp_f32_e32 v75, v75
	ds_read_b128 v[226:229], v179 offset:25216
	s_waitcnt lgkmcnt(7)
	v_mfma_f32_16x16x32_bf16 v[104:107], v[198:201], v[8:11], v[104:107]
	v_exp_f32_e32 v80, v80
	v_exp_f32_e32 v81, v81
	v_mfma_f32_16x16x32_bf16 v[108:111], v[198:201], v[16:19], v[108:111]
	v_exp_f32_e32 v82, v82
	s_waitcnt lgkmcnt(6)
	v_mfma_f32_16x16x32_bf16 v[112:115], v[202:205], v[8:11], v[112:115]
	v_exp_f32_e32 v83, v83
	v_mfma_f32_16x16x32_bf16 v[116:119], v[202:205], v[16:19], v[116:119]
	v_exp_f32_e32 v76, v76
	s_waitcnt lgkmcnt(5)
	v_mfma_f32_16x16x32_bf16 v[120:123], v[206:209], v[8:11], v[120:123]
	v_exp_f32_e32 v77, v77
	v_mfma_f32_16x16x32_bf16 v[124:127], v[206:209], v[16:19], v[124:127]
	v_exp_f32_e32 v78, v78
	v_exp_f32_e32 v79, v79
	s_waitcnt lgkmcnt(4)
	v_mfma_f32_16x16x32_bf16 v[128:131], v[210:213], v[8:11], v[128:131]
	v_exp_f32_e32 v84, v84
	v_mfma_f32_16x16x32_bf16 v[132:135], v[210:213], v[16:19], v[132:135]
	v_exp_f32_e32 v85, v85
	s_waitcnt lgkmcnt(3)
	v_mfma_f32_16x16x32_bf16 v[104:107], v[214:217], v[4:7], v[104:107]
	v_exp_f32_e32 v86, v86
	v_mfma_f32_16x16x32_bf16 v[108:111], v[214:217], v[0:3], v[108:111]
	v_exp_f32_e32 v87, v87
	s_waitcnt lgkmcnt(2)
	v_mfma_f32_16x16x32_bf16 v[112:115], v[218:221], v[4:7], v[112:115]
	v_cvt_pk_bf16_f32 v136, v72, v73
	v_cvt_pk_bf16_f32 v137, v74, v75
	v_mfma_f32_16x16x32_bf16 v[116:119], v[218:221], v[0:3], v[116:119]
	v_cvt_pk_bf16_f32 v138, v80, v81
	s_waitcnt lgkmcnt(1)
	v_mfma_f32_16x16x32_bf16 v[120:123], v[222:225], v[4:7], v[120:123]
	v_cvt_pk_bf16_f32 v139, v82, v83
	v_mfma_f32_16x16x32_bf16 v[124:127], v[222:225], v[0:3], v[124:127]
	v_cvt_pk_bf16_f32 v140, v76, v77
	s_waitcnt lgkmcnt(0)
	v_mfma_f32_16x16x32_bf16 v[128:131], v[226:229], v[4:7], v[128:131]
	v_cvt_pk_bf16_f32 v141, v78, v79
	v_mfma_f32_16x16x32_bf16 v[132:135], v[226:229], v[0:3], v[132:135]
	v_cvt_pk_bf16_f32 v142, v84, v85
	v_cvt_pk_bf16_f32 v143, v86, v87
	s_waitcnt lgkmcnt(0)
	s_barrier
	s_mov_b32 s18, s15
	s_mov_b32 s15, s12
	s_mov_b32 s12, s9
	s_mov_b32 s9, s18
	s_add_i32 s13, s13, 1
	s_cmp_lg_u32 s13, 16
	s_cbranch_scc1 .Lattn_b_loop
	global_load_dwordx4 v[230:233], v[164:165], off
	global_load_dwordx4 v[234:237], v[166:167], off
	global_load_dwordx4 v[238:241], v[168:169], off
	global_load_dwordx4 v[242:245], v[170:171], off
	global_load_dwordx4 v[246:249], v[172:173], off
	v_lshl_add_u64 v[164:165], v[164:165], 0, s[26:27]
	v_lshl_add_u64 v[166:167], v[166:167], 0, s[26:27]
	v_lshl_add_u64 v[168:169], v[168:169], 0, s[16:17]
	v_lshl_add_u64 v[170:171], v[170:171], 0, s[16:17]
	v_lshl_add_u64 v[172:173], v[172:173], 0, s[16:17]
	v_add_u32_e32 v184, s9, v159
	v_add_u32_e32 v185, s9, v161
	v_add_u32_e32 v186, s9, v163
	v_add_u32_e32 v187, s9, v160
	v_add_u32_e32 v188, s9, v162
	v_add3_u32 v180, s15, v176, v177
	ds_read_b64 v[198:199], v180 offset:28672
	ds_read_b64 v[200:201], v180 offset:28704
	ds_read_b64 v[202:203], v180 offset:33024
	ds_read_b64 v[204:205], v180 offset:33056
	ds_read_b64 v[206:207], v180 offset:37376
	ds_read_b64 v[208:209], v180 offset:37408
	ds_read_b64 v[210:211], v180 offset:41728
	ds_read_b64 v[212:213], v180 offset:41760
	ds_read_b64 v[214:215], v180 offset:28736
	ds_read_b64 v[216:217], v180 offset:28768
	ds_read_b64 v[218:219], v180 offset:33088
	ds_read_b64 v[220:221], v180 offset:33120
	ds_read_b64 v[222:223], v180 offset:37440
	ds_read_b64 v[224:225], v180 offset:37472
	ds_read_b64 v[226:227], v180 offset:41792
	ds_read_b64 v[228:229], v180 offset:41824
	v_mfma_f32_16x16x32_bf16 v[68:71], v[152:155], v[136:139], v[68:71]
	v_exp_f32_e32 v88, v88
	v_exp_f32_e32 v89, v89
	v_mfma_f32_16x16x32_bf16 v[56:59], v[152:155], v[140:143], v[56:59]
	v_exp_f32_e32 v90, v90
	v_exp_f32_e32 v91, v91
	s_waitcnt lgkmcnt(8)
; DEV float ex2(float x) { return __builtin_amdgcn_exp2f(x); }
; DEV void attn_item(const Params& p, int bl, int head, int q0, int nkeys, char* smem, int tid) {
;     ...
;       for (int kk = 0; kk < 2; ++kk) {
;         bf16x8 pb[2];
; #pragma unroll
;         for (int qt = 0; qt < 2; ++qt) {
;           const float e0 = ex2(s[2 * kk][qt][0]), e1 = ex2(s[2 * kk][qt][1]), e2 = ex2(s[2 * kk][qt][2]), e3 = ex2(s[2 * kk][qt][3]);
;           const float e4 = ex2(s[2 * kk + 1][qt][0]), e5 = ex2(s[2 * kk + 1][qt][1]), e6 = ex2(s[2 * kk + 1][qt][2]), e7 = ex2(s[2 * kk + 1][qt][3]);
;           u32x4 cw = {pack2(e0, e1), pack2(e2, e3), pack2(e4, e5), pack2(e6, e7)};
;           pb[qt] = __builtin_bit_cast(bf16x8, cw);
;         }
;         lacc[0] = __builtin_amdgcn_mfma_f32_16x16x32_bf16(ones, pb[0], lacc[0], 0, 0, 0);
;         lacc[1] = __builtin_amdgcn_mfma_f32_16x16x32_bf16(ones, pb[1], lacc[1], 0, 0, 0);
; #pragma unroll
;         for (int dvf = 0; dvf < 4; ++dvf) {
;           const char* vp = vb + (dvf * 16 + fr) * VROW + (hh * 64 + kk * 32 + fq * 4) * 2;
;           const uint2 h0 = *(const uint2*)vp, h1 = *(const uint2*)(vp + 32);
;           u32x4 vw = {h0.x, h0.y, h1.x, h1.y};
;           const bf16x8 va = __builtin_bit_cast(bf16x8, vw);
;           o[dvf][0] = __builtin_amdgcn_mfma_f32_16x16x32_bf16(va, pb[0], o[dvf][0], 0, 0, 0);
;           o[dvf][1] = __builtin_amdgcn_mfma_f32_16x16x32_bf16(va, pb[1], o[dvf][1], 0, 0, 0);
;         }
	v_mfma_f32_16x16x32_bf16 v[32:35], v[198:201], v[136:139], v[32:35]
	v_exp_f32_e32 v96, v96
	v_exp_f32_e32 v97, v97
	v_mfma_f32_16x16x32_bf16 v[36:39], v[198:201], v[140:143], v[36:39]
	v_exp_f32_e32 v98, v98
	v_exp_f32_e32 v99, v99
	v_exp_f32_e32 v92, v92
	v_mfma_f32_16x16x32_bf16 v[40:43], v[202:205], v[136:139], v[40:43]
	v_exp_f32_e32 v93, v93
	v_exp_f32_e32 v94, v94
	v_mfma_f32_16x16x32_bf16 v[60:63], v[202:205], v[140:143], v[60:63]
	v_exp_f32_e32 v95, v95
	v_exp_f32_e32 v100, v100
	v_exp_f32_e32 v101, v101
	v_mfma_f32_16x16x32_bf16 v[44:47], v[206:209], v[136:139], v[44:47]
	v_exp_f32_e32 v102, v102
	v_exp_f32_e32 v103, v103
	v_mfma_f32_16x16x32_bf16 v[64:67], v[206:209], v[140:143], v[64:67]
	v_cvt_pk_bf16_f32 v144, v88, v89
	v_cvt_pk_bf16_f32 v145, v90, v91
	v_cvt_pk_bf16_f32 v146, v96, v97
	v_mfma_f32_16x16x32_bf16 v[48:51], v[210:213], v[136:139], v[48:51]
	v_cvt_pk_bf16_f32 v147, v98, v99
	v_cvt_pk_bf16_f32 v148, v92, v93
	v_mfma_f32_16x16x32_bf16 v[52:55], v[210:213], v[140:143], v[52:55]
	v_cvt_pk_bf16_f32 v149, v94, v95
	v_cvt_pk_bf16_f32 v150, v100, v101
	v_cvt_pk_bf16_f32 v151, v102, v103
	ds_read_b64 v[198:199], v180 offset:28800
	ds_read_b64 v[200:201], v180 offset:28832
	ds_read_b64 v[202:203], v180 offset:33152
	ds_read_b64 v[204:205], v180 offset:33184
	ds_read_b64 v[206:207], v180 offset:37504
	ds_read_b64 v[208:209], v180 offset:37536
	ds_read_b64 v[210:211], v180 offset:41856
	ds_read_b64 v[212:213], v180 offset:41888
	s_nop 1
	v_mfma_f32_16x16x32_bf16 v[68:71], v[152:155], v[144:147], v[68:71]
	v_exp_f32_e32 v104, v104
	v_exp_f32_e32 v105, v105
	v_mfma_f32_16x16x32_bf16 v[56:59], v[152:155], v[148:151], v[56:59]
	v_exp_f32_e32 v106, v106
	v_exp_f32_e32 v107, v107
	s_waitcnt lgkmcnt(8)
	v_mfma_f32_16x16x32_bf16 v[32:35], v[214:217], v[144:147], v[32:35]
	v_exp_f32_e32 v112, v112
	v_exp_f32_e32 v113, v113
	v_mfma_f32_16x16x32_bf16 v[36:39], v[214:217], v[148:151], v[36:39]
	v_exp_f32_e32 v114, v114
	v_exp_f32_e32 v115, v115
	v_exp_f32_e32 v108, v108
	v_mfma_f32_16x16x32_bf16 v[40:43], v[218:221], v[144:147], v[40:43]
	v_exp_f32_e32 v109, v109
	v_exp_f32_e32 v110, v110
	v_mfma_f32_16x16x32_bf16 v[60:63], v[218:221], v[148:151], v[60:63]
	v_exp_f32_e32 v111, v111
	v_exp_f32_e32 v116, v116
	v_exp_f32_e32 v117, v117
	v_mfma_f32_16x16x32_bf16 v[44:47], v[222:225], v[144:147], v[44:47]
	v_exp_f32_e32 v118, v118
	v_exp_f32_e32 v119, v119
	v_mfma_f32_16x16x32_bf16 v[64:67], v[222:225], v[148:151], v[64:67]
	v_cvt_pk_bf16_f32 v136, v104, v105
	v_cvt_pk_bf16_f32 v137, v106, v107
	v_cvt_pk_bf16_f32 v138, v112, v113
	v_mfma_f32_16x16x32_bf16 v[48:51], v[226:229], v[144:147], v[48:51]
	v_cvt_pk_bf16_f32 v139, v114, v115
	v_cvt_pk_bf16_f32 v140, v108, v109
	v_mfma_f32_16x16x32_bf16 v[52:55], v[226:229], v[148:151], v[52:55]
	v_cvt_pk_bf16_f32 v141, v110, v111
	v_cvt_pk_bf16_f32 v142, v116, v117
	v_cvt_pk_bf16_f32 v143, v118, v119
	ds_read_b64 v[214:215], v180 offset:28864
	ds_read_b64 v[216:217], v180 offset:28896
	ds_read_b64 v[218:219], v180 offset:33216
	ds_read_b64 v[220:221], v180 offset:33248
	ds_read_b64 v[222:223], v180 offset:37568
	ds_read_b64 v[224:225], v180 offset:37600
	ds_read_b64 v[226:227], v180 offset:41920
	ds_read_b64 v[228:229], v180 offset:41952
	s_nop 1
	v_mfma_f32_16x16x32_bf16 v[68:71], v[152:155], v[136:139], v[68:71]
	v_exp_f32_e32 v120, v120
	v_exp_f32_e32 v121, v121
	v_mfma_f32_16x16x32_bf16 v[56:59], v[152:155], v[140:143], v[56:59]
	v_exp_f32_e32 v122, v122
	v_exp_f32_e32 v123, v123
	s_waitcnt lgkmcnt(8)
	v_mfma_f32_16x16x32_bf16 v[32:35], v[198:201], v[136:139], v[32:35]
	v_exp_f32_e32 v128, v128
	v_exp_f32_e32 v129, v129
	v_mfma_f32_16x16x32_bf16 v[36:39], v[198:201], v[140:143], v[36:39]
	v_exp_f32_e32 v130, v130
	v_exp_f32_e32 v131, v131
	v_exp_f32_e32 v124, v124
	v_mfma_f32_16x16x32_bf16 v[40:43], v[202:205], v[136:139], v[40:43]
	v_exp_f32_e32 v125, v125
	v_exp_f32_e32 v126, v126
	v_mfma_f32_16x16x32_bf16 v[60:63], v[202:205], v[140:143], v[60:63]
	v_exp_f32_e32 v127, v127
	v_exp_f32_e32 v132, v132
	v_exp_f32_e32 v133, v133
	v_mfma_f32_16x16x32_bf16 v[44:47], v[206:209], v[136:139], v[44:47]
	v_exp_f32_e32 v134, v134
	v_exp_f32_e32 v135, v135
	v_mfma_f32_16x16x32_bf16 v[64:67], v[206:209], v[140:143], v[64:67]
	v_cvt_pk_bf16_f32 v144, v120, v121
	v_cvt_pk_bf16_f32 v145, v122, v123
	v_cvt_pk_bf16_f32 v146, v128, v129
	v_mfma_f32_16x16x32_bf16 v[48:51], v[210:213], v[136:139], v[48:51]
	v_cvt_pk_bf16_f32 v147, v130, v131
	v_cvt_pk_bf16_f32 v148, v124, v125
	v_mfma_f32_16x16x32_bf16 v[52:55], v[210:213], v[140:143], v[52:55]
	v_cvt_pk_bf16_f32 v149, v126, v127
	v_cvt_pk_bf16_f32 v150, v132, v133
	v_cvt_pk_bf16_f32 v151, v134, v135
	s_nop 1
	v_mfma_f32_16x16x32_bf16 v[68:71], v[152:155], v[144:147], v[68:71]
	v_mfma_f32_16x16x32_bf16 v[56:59], v[152:155], v[148:151], v[56:59]
	s_waitcnt lgkmcnt(0)
	v_mfma_f32_16x16x32_bf16 v[32:35], v[214:217], v[144:147], v[32:35]
	v_mfma_f32_16x16x32_bf16 v[36:39], v[214:217], v[148:151], v[36:39]
	v_mfma_f32_16x16x32_bf16 v[40:43], v[218:221], v[144:147], v[40:43]
	v_mfma_f32_16x16x32_bf16 v[60:63], v[218:221], v[148:151], v[60:63]
	v_mfma_f32_16x16x32_bf16 v[44:47], v[222:225], v[144:147], v[44:47]
	v_mfma_f32_16x16x32_bf16 v[64:67], v[222:225], v[148:151], v[64:67]
	v_mfma_f32_16x16x32_bf16 v[48:51], v[226:229], v[144:147], v[48:51]
	v_mfma_f32_16x16x32_bf16 v[52:55], v[226:229], v[148:151], v[52:55]
	s_waitcnt vmcnt(0)
; DEV float ex2(float x) { return __builtin_amdgcn_exp2f(x); }
; DEV void attn_item(const Params& p, int bl, int head, int q0, int nkeys, char* smem, int tid) {
;     ...
;     for (int hh = 0; hh < 2; ++hh) {
;       f32x4 s[4][2];
; #pragma unroll
;       for (int kf = 0; kf < 4; ++kf) {
; #pragma unroll
;         for (int ks = 0; ks < 3; ++ks) {
;           bf16x8 a = *(const bf16x8*)(kb + (hh * 64 + kf * 16 + fr) * KROW + ks * 64 + fq * 16);
;           s[kf][0] = __builtin_amdgcn_mfma_f32_16x16x32_bf16(a, qf[0][ks], ks == 0 ? negm[0] : s[kf][0], 0, 0, 0);
;           s[kf][1] = __builtin_amdgcn_mfma_f32_16x16x32_bf16(a, qf[1][ks], ks == 0 ? negm[1] : s[kf][1], 0, 0, 0);
;         }
;       }
; #pragma unroll
;       for (int kk = 0; kk < 2; ++kk) {
;         bf16x8 pb[2];
; #pragma unroll
;         for (int qt = 0; qt < 2; ++qt) {
;           const float e0 = ex2(s[2 * kk][qt][0]), e1 = ex2(s[2 * kk][qt][1]), e2 = ex2(s[2 * kk][qt][2]), e3 = ex2(s[2 * kk][qt][3]);
;           const float e4 = ex2(s[2 * kk + 1][qt][0]), e5 = ex2(s[2 * kk + 1][qt][1]), e6 = ex2(s[2 * kk + 1][qt][2]), e7 = ex2(s[2 * kk + 1][qt][3]);
;           u32x4 cw = {pack2(e0, e1), pack2(e2, e3), pack2(e4, e5), pack2(e6, e7)};
;           pb[qt] = __builtin_bit_cast(bf16x8, cw);
;         }
;         lacc[0] = __builtin_amdgcn_mfma_f32_16x16x32_bf16(ones, pb[0], lacc[0], 0, 0, 0);
;         lacc[1] = __builtin_amdgcn_mfma_f32_16x16x32_bf16(ones, pb[1], lacc[1], 0, 0, 0);
; #pragma unroll
;         for (int dvf = 0; dvf < 4; ++dvf) {
;           const char* vp = vb + (dvf * 16 + fr) * VROW + (hh * 64 + kk * 32 + fq * 4) * 2;
;           const uint2 h0 = *(const uint2*)vp, h1 = *(const uint2*)(vp + 32);
;           u32x4 vw = {h0.x, h0.y, h1.x, h1.y};
;           const bf16x8 va = __builtin_bit_cast(bf16x8, vw);
;           o[dvf][0] = __builtin_amdgcn_mfma_f32_16x16x32_bf16(va, pb[0], o[dvf][0], 0, 0, 0);
;           o[dvf][1] = __builtin_amdgcn_mfma_f32_16x16x32_bf16(va, pb[1], o[dvf][1], 0, 0, 0);
;         }
;       }
;     }
;     if (t + 1 < nt) {
;       char* nb = smem + ((t + 1) & 1) * ASTG;
; #pragma unroll
;       for (int i = 0; i < 3; ++i) *(u32x4*)(nb + koff[i]) = kr[i];
; #pragma unroll
;       for (int i = 0; i < 2; ++i) *(u32x4*)(nb + KBYTES + voffl[i]) = vr[i];
;     }
;     __syncthreads();
	ds_write_b128 v184, v[238:241]
	ds_write_b128 v185, v[242:245]
	ds_write_b128 v186, v[246:249]
	ds_write_b128 v187, v[230:233] offset:26624
	ds_write_b128 v188, v[234:237] offset:26624
	v_add3_u32 v179, s12, v156, v181
	ds_read_b128 v[198:201], v179
	ds_read_b128 v[202:205], v179 offset:3584
	ds_read_b128 v[206:209], v179 offset:7168
	ds_read_b128 v[210:213], v179 offset:10752
	ds_read_b128 v[214:217], v179 offset:64
	ds_read_b128 v[218:221], v179 offset:3648
	ds_read_b128 v[222:225], v179 offset:7232
	ds_read_b128 v[226:229], v179 offset:10816
	s_waitcnt lgkmcnt(7)
	v_mfma_f32_16x16x32_bf16 v[72:75], v[198:201], v[12:15], v[24:27]
	v_mfma_f32_16x16x32_bf16 v[76:79], v[198:201], v[20:23], v[28:31]
	ds_read_b128 v[198:201], v179 offset:128
	s_waitcnt lgkmcnt(7)
	v_mfma_f32_16x16x32_bf16 v[80:83], v[202:205], v[12:15], v[24:27]
	v_mfma_f32_16x16x32_bf16 v[84:87], v[202:205], v[20:23], v[28:31]
	ds_read_b128 v[202:205], v179 offset:3712
	s_waitcnt lgkmcnt(7)
	v_mfma_f32_16x16x32_bf16 v[88:91], v[206:209], v[12:15], v[24:27]
	v_mfma_f32_16x16x32_bf16 v[92:95], v[206:209], v[20:23], v[28:31]
	ds_read_b128 v[206:209], v179 offset:7296
	s_waitcnt lgkmcnt(7)
	v_mfma_f32_16x16x32_bf16 v[96:99], v[210:213], v[12:15], v[24:27]
	v_mfma_f32_16x16x32_bf16 v[100:103], v[210:213], v[20:23], v[28:31]
	ds_read_b128 v[210:213], v179 offset:10880
	s_waitcnt lgkmcnt(7)
	v_mfma_f32_16x16x32_bf16 v[72:75], v[214:217], v[8:11], v[72:75]
	v_mfma_f32_16x16x32_bf16 v[76:79], v[214:217], v[16:19], v[76:79]
	ds_read_b128 v[214:217], v179 offset:14336
	s_waitcnt lgkmcnt(7)
	v_mfma_f32_16x16x32_bf16 v[80:83], v[218:221], v[8:11], v[80:83]
	v_mfma_f32_16x16x32_bf16 v[84:87], v[218:221], v[16:19], v[84:87]
	ds_read_b128 v[218:221], v179 offset:17920
	s_waitcnt lgkmcnt(7)
	v_mfma_f32_16x16x32_bf16 v[88:91], v[222:225], v[8:11], v[88:91]
	v_mfma_f32_16x16x32_bf16 v[92:95], v[222:225], v[16:19], v[92:95]
	ds_read_b128 v[222:225], v179 offset:21504
	s_waitcnt lgkmcnt(7)
	v_mfma_f32_16x16x32_bf16 v[96:99], v[226:229], v[8:11], v[96:99]
	v_mfma_f32_16x16x32_bf16 v[100:103], v[226:229], v[16:19], v[100:103]
	ds_read_b128 v[226:229], v179 offset:25088
	s_waitcnt lgkmcnt(7)
	v_mfma_f32_16x16x32_bf16 v[72:75], v[198:201], v[4:7], v[72:75]
	v_mfma_f32_16x16x32_bf16 v[76:79], v[198:201], v[0:3], v[76:79]
	ds_read_b128 v[198:201], v179 offset:14400
	s_waitcnt lgkmcnt(7)
	v_mfma_f32_16x16x32_bf16 v[80:83], v[202:205], v[4:7], v[80:83]
	v_mfma_f32_16x16x32_bf16 v[84:87], v[202:205], v[0:3], v[84:87]
	ds_read_b128 v[202:205], v179 offset:17984
	s_waitcnt lgkmcnt(7)
	v_mfma_f32_16x16x32_bf16 v[88:91], v[206:209], v[4:7], v[88:91]
	v_mfma_f32_16x16x32_bf16 v[92:95], v[206:209], v[0:3], v[92:95]
	ds_read_b128 v[206:209], v179 offset:21568
	s_waitcnt lgkmcnt(7)
	v_mfma_f32_16x16x32_bf16 v[96:99], v[210:213], v[4:7], v[96:99]
	v_mfma_f32_16x16x32_bf16 v[100:103], v[210:213], v[0:3], v[100:103]
	ds_read_b128 v[210:213], v179 offset:25152
	s_waitcnt lgkmcnt(7)
	v_mfma_f32_16x16x32_bf16 v[104:107], v[214:217], v[12:15], v[24:27]
	v_mfma_f32_16x16x32_bf16 v[108:111], v[214:217], v[20:23], v[28:31]
	ds_read_b128 v[214:217], v179 offset:14464
	s_waitcnt lgkmcnt(7)
	v_mfma_f32_16x16x32_bf16 v[112:115], v[218:221], v[12:15], v[24:27]
	v_mfma_f32_16x16x32_bf16 v[116:119], v[218:221], v[20:23], v[28:31]
	ds_read_b128 v[218:221], v179 offset:18048
	s_waitcnt lgkmcnt(7)
	v_mfma_f32_16x16x32_bf16 v[120:123], v[222:225], v[12:15], v[24:27]
	v_exp_f32_e32 v72, v72
	v_mfma_f32_16x16x32_bf16 v[124:127], v[222:225], v[20:23], v[28:31]
	v_exp_f32_e32 v73, v73
	ds_read_b128 v[222:225], v179 offset:21632
	s_waitcnt lgkmcnt(7)
	v_mfma_f32_16x16x32_bf16 v[128:131], v[226:229], v[12:15], v[24:27]
	v_exp_f32_e32 v74, v74
	v_mfma_f32_16x16x32_bf16 v[132:135], v[226:229], v[20:23], v[28:31]
	v_exp_f32_e32 v75, v75
	ds_read_b128 v[226:229], v179 offset:25216
	s_waitcnt lgkmcnt(7)
	v_mfma_f32_16x16x32_bf16 v[104:107], v[198:201], v[8:11], v[104:107]
	v_exp_f32_e32 v80, v80
	v_exp_f32_e32 v81, v81
	v_mfma_f32_16x16x32_bf16 v[108:111], v[198:201], v[16:19], v[108:111]
	v_exp_f32_e32 v82, v82
	s_waitcnt lgkmcnt(6)
	v_mfma_f32_16x16x32_bf16 v[112:115], v[202:205], v[8:11], v[112:115]
	v_exp_f32_e32 v83, v83
	v_mfma_f32_16x16x32_bf16 v[116:119], v[202:205], v[16:19], v[116:119]
	v_exp_f32_e32 v76, v76
	s_waitcnt lgkmcnt(5)
	v_mfma_f32_16x16x32_bf16 v[120:123], v[206:209], v[8:11], v[120:123]
	v_exp_f32_e32 v77, v77
	v_mfma_f32_16x16x32_bf16 v[124:127], v[206:209], v[16:19], v[124:127]
	v_exp_f32_e32 v78, v78
	v_exp_f32_e32 v79, v79
	s_waitcnt lgkmcnt(4)
	v_mfma_f32_16x16x32_bf16 v[128:131], v[210:213], v[8:11], v[128:131]
	v_exp_f32_e32 v84, v84
	v_mfma_f32_16x16x32_bf16 v[132:135], v[210:213], v[16:19], v[132:135]
	v_exp_f32_e32 v85, v85
	s_waitcnt lgkmcnt(3)
	v_mfma_f32_16x16x32_bf16 v[104:107], v[214:217], v[4:7], v[104:107]
	v_exp_f32_e32 v86, v86
	v_mfma_f32_16x16x32_bf16 v[108:111], v[214:217], v[0:3], v[108:111]
	v_exp_f32_e32 v87, v87
	s_waitcnt lgkmcnt(2)
	v_mfma_f32_16x16x32_bf16 v[112:115], v[218:221], v[4:7], v[112:115]
	v_cvt_pk_bf16_f32 v136, v72, v73
	v_cvt_pk_bf16_f32 v137, v74, v75
	v_mfma_f32_16x16x32_bf16 v[116:119], v[218:221], v[0:3], v[116:119]
	v_cvt_pk_bf16_f32 v138, v80, v81
	s_waitcnt lgkmcnt(1)
	v_mfma_f32_16x16x32_bf16 v[120:123], v[222:225], v[4:7], v[120:123]
	v_cvt_pk_bf16_f32 v139, v82, v83
	v_mfma_f32_16x16x32_bf16 v[124:127], v[222:225], v[0:3], v[124:127]
	v_cvt_pk_bf16_f32 v140, v76, v77
	s_waitcnt lgkmcnt(0)
	v_mfma_f32_16x16x32_bf16 v[128:131], v[226:229], v[4:7], v[128:131]
	v_cvt_pk_bf16_f32 v141, v78, v79
	v_mfma_f32_16x16x32_bf16 v[132:135], v[226:229], v[0:3], v[132:135]
	v_cvt_pk_bf16_f32 v142, v84, v85
	v_cvt_pk_bf16_f32 v143, v86, v87
	s_waitcnt lgkmcnt(0)
	s_barrier
; DEV float ex2(float x) { return __builtin_amdgcn_exp2f(x); }
; DEV void attn_item(const Params& p, int bl, int head, int q0, int nkeys, char* smem, int tid) {
;     ...
;       for (int kk = 0; kk < 2; ++kk) {
;         bf16x8 pb[2];
; #pragma unroll
;         for (int qt = 0; qt < 2; ++qt) {
;           const float e0 = ex2(s[2 * kk][qt][0]), e1 = ex2(s[2 * kk][qt][1]), e2 = ex2(s[2 * kk][qt][2]), e3 = ex2(s[2 * kk][qt][3]);
;           const float e4 = ex2(s[2 * kk + 1][qt][0]), e5 = ex2(s[2 * kk + 1][qt][1]), e6 = ex2(s[2 * kk + 1][qt][2]), e7 = ex2(s[2 * kk + 1][qt][3]);
;           u32x4 cw = {pack2(e0, e1), pack2(e2, e3), pack2(e4, e5), pack2(e6, e7)};
;           pb[qt] = __builtin_bit_cast(bf16x8, cw);
;         }
;         lacc[0] = __builtin_amdgcn_mfma_f32_16x16x32_bf16(ones, pb[0], lacc[0], 0, 0, 0);
;         lacc[1] = __builtin_amdgcn_mfma_f32_16x16x32_bf16(ones, pb[1], lacc[1], 0, 0, 0);
; #pragma unroll
;         for (int dvf = 0; dvf < 4; ++dvf) {
;           const char* vp = vb + (dvf * 16 + fr) * VROW + (hh * 64 + kk * 32 + fq * 4) * 2;
;           const uint2 h0 = *(const uint2*)vp, h1 = *(const uint2*)(vp + 32);
;           u32x4 vw = {h0.x, h0.y, h1.x, h1.y};
;           const bf16x8 va = __builtin_bit_cast(bf16x8, vw);
;           o[dvf][0] = __builtin_amdgcn_mfma_f32_16x16x32_bf16(va, pb[0], o[dvf][0], 0, 0, 0);
;           o[dvf][1] = __builtin_amdgcn_mfma_f32_16x16x32_bf16(va, pb[1], o[dvf][1], 0, 0, 0);
;         }
;       }
;     }
;     if (t + 1 < nt) {
;       char* nb = smem + ((t + 1) & 1) * ASTG;
; #pragma unroll
;       for (int i = 0; i < 3; ++i) *(u32x4*)(nb + koff[i]) = kr[i];
; #pragma unroll
;       for (int i = 0; i < 2; ++i) *(u32x4*)(nb + KBYTES + voffl[i]) = vr[i];
;     }
;     __syncthreads();
;   }
	s_mov_b32 s18, s15
	s_mov_b32 s15, s12
	s_mov_b32 s12, s9
	s_mov_b32 s9, s18
	s_add_i32 s13, s13, 1
	v_add3_u32 v180, s15, v176, v177
	ds_read_b64 v[198:199], v180 offset:28672
	ds_read_b64 v[200:201], v180 offset:28704
	ds_read_b64 v[202:203], v180 offset:33024
	ds_read_b64 v[204:205], v180 offset:33056
	ds_read_b64 v[206:207], v180 offset:37376
	ds_read_b64 v[208:209], v180 offset:37408
	ds_read_b64 v[210:211], v180 offset:41728
	ds_read_b64 v[212:213], v180 offset:41760
	ds_read_b64 v[214:215], v180 offset:28736
	ds_read_b64 v[216:217], v180 offset:28768
	ds_read_b64 v[218:219], v180 offset:33088
	ds_read_b64 v[220:221], v180 offset:33120
	ds_read_b64 v[222:223], v180 offset:37440
	ds_read_b64 v[224:225], v180 offset:37472
	ds_read_b64 v[226:227], v180 offset:41792
	ds_read_b64 v[228:229], v180 offset:41824
	v_mfma_f32_16x16x32_bf16 v[68:71], v[152:155], v[136:139], v[68:71]
	v_exp_f32_e32 v88, v88
	v_exp_f32_e32 v89, v89
	v_mfma_f32_16x16x32_bf16 v[56:59], v[152:155], v[140:143], v[56:59]
	v_exp_f32_e32 v90, v90
	v_exp_f32_e32 v91, v91
	s_waitcnt lgkmcnt(8)
	v_mfma_f32_16x16x32_bf16 v[32:35], v[198:201], v[136:139], v[32:35]
	v_exp_f32_e32 v96, v96
	v_exp_f32_e32 v97, v97
	v_mfma_f32_16x16x32_bf16 v[36:39], v[198:201], v[140:143], v[36:39]
	v_exp_f32_e32 v98, v98
	v_exp_f32_e32 v99, v99
	v_exp_f32_e32 v92, v92
	v_mfma_f32_16x16x32_bf16 v[40:43], v[202:205], v[136:139], v[40:43]
	v_exp_f32_e32 v93, v93
	v_exp_f32_e32 v94, v94
	v_mfma_f32_16x16x32_bf16 v[60:63], v[202:205], v[140:143], v[60:63]
	v_exp_f32_e32 v95, v95
	v_exp_f32_e32 v100, v100
	v_exp_f32_e32 v101, v101
	v_mfma_f32_16x16x32_bf16 v[44:47], v[206:209], v[136:139], v[44:47]
	v_exp_f32_e32 v102, v102
	v_exp_f32_e32 v103, v103
	v_mfma_f32_16x16x32_bf16 v[64:67], v[206:209], v[140:143], v[64:67]
	v_cvt_pk_bf16_f32 v144, v88, v89
	v_cvt_pk_bf16_f32 v145, v90, v91
	v_cvt_pk_bf16_f32 v146, v96, v97
	v_mfma_f32_16x16x32_bf16 v[48:51], v[210:213], v[136:139], v[48:51]
	v_cvt_pk_bf16_f32 v147, v98, v99
	v_cvt_pk_bf16_f32 v148, v92, v93
	v_mfma_f32_16x16x32_bf16 v[52:55], v[210:213], v[140:143], v[52:55]
	v_cvt_pk_bf16_f32 v149, v94, v95
	v_cvt_pk_bf16_f32 v150, v100, v101
	v_cvt_pk_bf16_f32 v151, v102, v103
	ds_read_b64 v[198:199], v180 offset:28800
	ds_read_b64 v[200:201], v180 offset:28832
	ds_read_b64 v[202:203], v180 offset:33152
	ds_read_b64 v[204:205], v180 offset:33184
	ds_read_b64 v[206:207], v180 offset:37504
	ds_read_b64 v[208:209], v180 offset:37536
	ds_read_b64 v[210:211], v180 offset:41856
	ds_read_b64 v[212:213], v180 offset:41888
	s_nop 1
	v_mfma_f32_16x16x32_bf16 v[68:71], v[152:155], v[144:147], v[68:71]
	v_exp_f32_e32 v104, v104
	v_exp_f32_e32 v105, v105
	v_mfma_f32_16x16x32_bf16 v[56:59], v[152:155], v[148:151], v[56:59]
	v_exp_f32_e32 v106, v106
	v_exp_f32_e32 v107, v107
	s_waitcnt lgkmcnt(8)
	v_mfma_f32_16x16x32_bf16 v[32:35], v[214:217], v[144:147], v[32:35]
	v_exp_f32_e32 v112, v112
	v_exp_f32_e32 v113, v113
	v_mfma_f32_16x16x32_bf16 v[36:39], v[214:217], v[148:151], v[36:39]
	v_exp_f32_e32 v114, v114
	v_exp_f32_e32 v115, v115
	v_exp_f32_e32 v108, v108
	v_mfma_f32_16x16x32_bf16 v[40:43], v[218:221], v[144:147], v[40:43]
	v_exp_f32_e32 v109, v109
	v_exp_f32_e32 v110, v110
	v_mfma_f32_16x16x32_bf16 v[60:63], v[218:221], v[148:151], v[60:63]
	v_exp_f32_e32 v111, v111
	v_exp_f32_e32 v116, v116
	v_exp_f32_e32 v117, v117
	v_mfma_f32_16x16x32_bf16 v[44:47], v[222:225], v[144:147], v[44:47]
	v_exp_f32_e32 v118, v118
	v_exp_f32_e32 v119, v119
	v_mfma_f32_16x16x32_bf16 v[64:67], v[222:225], v[148:151], v[64:67]
	v_cvt_pk_bf16_f32 v136, v104, v105
	v_cvt_pk_bf16_f32 v137, v106, v107
	v_cvt_pk_bf16_f32 v138, v112, v113
	v_mfma_f32_16x16x32_bf16 v[48:51], v[226:229], v[144:147], v[48:51]
	v_cvt_pk_bf16_f32 v139, v114, v115
	v_cvt_pk_bf16_f32 v140, v108, v109
	v_mfma_f32_16x16x32_bf16 v[52:55], v[226:229], v[148:151], v[52:55]
	v_cvt_pk_bf16_f32 v141, v110, v111
	v_cvt_pk_bf16_f32 v142, v116, v117
	v_cvt_pk_bf16_f32 v143, v118, v119
	ds_read_b64 v[214:215], v180 offset:28864
	ds_read_b64 v[216:217], v180 offset:28896
	ds_read_b64 v[218:219], v180 offset:33216
	ds_read_b64 v[220:221], v180 offset:33248
	ds_read_b64 v[222:223], v180 offset:37568
	ds_read_b64 v[224:225], v180 offset:37600
	ds_read_b64 v[226:227], v180 offset:41920
	ds_read_b64 v[228:229], v180 offset:41952
	s_nop 1
	v_mfma_f32_16x16x32_bf16 v[68:71], v[152:155], v[136:139], v[68:71]
	v_exp_f32_e32 v120, v120
	v_exp_f32_e32 v121, v121
	v_mfma_f32_16x16x32_bf16 v[56:59], v[152:155], v[140:143], v[56:59]
	v_exp_f32_e32 v122, v122
	v_exp_f32_e32 v123, v123
	s_waitcnt lgkmcnt(8)
	v_mfma_f32_16x16x32_bf16 v[32:35], v[198:201], v[136:139], v[32:35]
	v_exp_f32_e32 v128, v128
	v_exp_f32_e32 v129, v129
	v_mfma_f32_16x16x32_bf16 v[36:39], v[198:201], v[140:143], v[36:39]
	v_exp_f32_e32 v130, v130
	v_exp_f32_e32 v131, v131
	v_exp_f32_e32 v124, v124
	v_mfma_f32_16x16x32_bf16 v[40:43], v[202:205], v[136:139], v[40:43]
	v_exp_f32_e32 v125, v125
	v_exp_f32_e32 v126, v126
	v_mfma_f32_16x16x32_bf16 v[60:63], v[202:205], v[140:143], v[60:63]
	v_exp_f32_e32 v127, v127
	v_exp_f32_e32 v132, v132
	v_exp_f32_e32 v133, v133
	v_mfma_f32_16x16x32_bf16 v[44:47], v[206:209], v[136:139], v[44:47]
	v_exp_f32_e32 v134, v134
	v_exp_f32_e32 v135, v135
	v_mfma_f32_16x16x32_bf16 v[64:67], v[206:209], v[140:143], v[64:67]
	v_cvt_pk_bf16_f32 v144, v120, v121
	v_cvt_pk_bf16_f32 v145, v122, v123
	v_cvt_pk_bf16_f32 v146, v128, v129
	v_mfma_f32_16x16x32_bf16 v[48:51], v[210:213], v[136:139], v[48:51]
	v_cvt_pk_bf16_f32 v147, v130, v131
	v_cvt_pk_bf16_f32 v148, v124, v125
	v_mfma_f32_16x16x32_bf16 v[52:55], v[210:213], v[140:143], v[52:55]
	v_cvt_pk_bf16_f32 v149, v126, v127
	v_cvt_pk_bf16_f32 v150, v132, v133
	v_cvt_pk_bf16_f32 v151, v134, v135
	s_nop 1
	v_mfma_f32_16x16x32_bf16 v[68:71], v[152:155], v[144:147], v[68:71]
	v_mfma_f32_16x16x32_bf16 v[56:59], v[152:155], v[148:151], v[56:59]
	s_waitcnt lgkmcnt(0)
	v_mfma_f32_16x16x32_bf16 v[32:35], v[214:217], v[144:147], v[32:35]
	v_mfma_f32_16x16x32_bf16 v[36:39], v[214:217], v[148:151], v[36:39]
	v_mfma_f32_16x16x32_bf16 v[40:43], v[218:221], v[144:147], v[40:43]
	v_mfma_f32_16x16x32_bf16 v[60:63], v[218:221], v[148:151], v[60:63]
	v_mfma_f32_16x16x32_bf16 v[44:47], v[222:225], v[144:147], v[44:47]
	v_mfma_f32_16x16x32_bf16 v[64:67], v[222:225], v[148:151], v[64:67]
	v_mfma_f32_16x16x32_bf16 v[48:51], v[226:229], v[144:147], v[48:51]
	v_mfma_f32_16x16x32_bf16 v[52:55], v[226:229], v[148:151], v[52:55]
	s_waitcnt lgkmcnt(0)
	s_setprio 0
